# plus: q/k natural-layout epilogue stores merged to 16 bytes via permlane16_swap on a scratch copy
# speedup vs baseline: 1.0090x; 1.0049x over previous
; #define PG8_STAGE(bufoff, gbase, voff) do { _Pragma("unroll") for (int _i = 0; _i < 2; ++_i) \
;         __builtin_amdgcn_global_load_lds((const unsigned*)((const char*)(gbase) + (voff)[_i]), (LAS unsigned*)(lds + (bufoff) + ldsw + _i * 8192), 16, 0, 0); } while (0)
; #define PG8_LDA(dst, b, h) do { _Pragma("unroll") for (int m = 0; m < 4; ++m) _Pragma("unroll") for (int k = 0; k < 2; ++k) dst[m][k] = *(const LAS bf16x8*)(lds + PG8_SA(b, h) + aoff + m * 2048 + k * 1024); } while (0)
; #define PG8_WAIT_V(n) asm volatile("s_waitcnt vmcnt(" #n ")" ::: "memory")
; #define PG8_WAIT_L(n) asm volatile("s_waitcnt lgkmcnt(" #n ")" ::: "memory")
; template <class Epi>
; __device__ __forceinline__ void gemm_phase(LAS unsigned char* lds, const Gemm g, const Order& S, KP kp, int code, int wv) {
;     ...
;         for (int t = 0; t < nt; t += 2) {
;             const bool last = (t == nt - 2);
;             const char* a1 = cA + (size_t)(t + 1) * kstep;
;             const char* a2 = last ? nA : cA + (size_t)(t + 2) * kstep; const char* b2 = last ? nB : cB + (size_t)(t + 2) * kstep;
;             const char* a3 = a2 + kstep; const char* b3 = b2 + kstep;
;             PG8_LDB(B0, 0, 0); PG8_SCHED; PG8_LDA(At, 0, 0); PG8_STAGE(PG8_SA(1, 1), a1 + hstepA, voffA);
;             PG8_WAIT_L(8); PG8_BAR; PG8_WAIT_L(0); PG8_MMA(0, 0, At, B0); PG8_BAR; PG8_SCHED;
;             PG8_LDB(B1, 0, 1); PG8_STAGE(PG8_SB(0, 0), b2, voffB);
;             PG8_BAR; PG8_WAIT_L(0); PG8_MMA(0, 1, At, B1); PG8_BAR;
;             PG8_LDA(At, 0, 1); PG8_STAGE(PG8_SA(0, 0), a2, voffA);
;             PG8_BAR; PG8_WAIT_L(0); PG8_MMA(1, 0, At, B0); PG8_BAR; PG8_SCHED;
;             PG8_STAGE(PG8_SB(0, 1), b2 + hstepB, voffB);
;             PG8_WAIT_V(6); PG8_BAR; PG8_MMA(1, 1, At, B1); PG8_BAR;
;             PG8_LDB(B0, 1, 0); PG8_SCHED; PG8_LDA(At, 1, 0); PG8_STAGE(PG8_SA(0, 1), a2 + hstepA, voffA);
;             PG8_WAIT_L(8); PG8_BAR; PG8_WAIT_L(0); PG8_MMA(0, 0, At, B0); PG8_BAR; PG8_SCHED;
;             PG8_LDB(B1, 1, 1); PG8_STAGE(PG8_SB(1, 0), b3, voffB);
;             PG8_BAR; PG8_WAIT_L(0); PG8_MMA(0, 1, At, B1); PG8_BAR;
;             PG8_LDA(At, 1, 1); PG8_STAGE(PG8_SA(1, 0), a3, voffA);
;             PG8_BAR; PG8_WAIT_L(0); PG8_MMA(1, 0, At, B0); PG8_BAR; PG8_SCHED;
;             PG8_STAGE(PG8_SB(1, 1), b3 + hstepB, voffB);
;             PG8_WAIT_V(6); PG8_BAR; PG8_MMA(1, 1, At, B1); PG8_BAR;
.LBB0_136:
	s_add_u32 s6, s4, 0xfff80080
	s_addc_u32 s7, s5, -1
	s_add_i32 s19, 0, 0x10000
	v_add_u32_e32 v0, s19, v145
	ds_read_b128 v[130:133], v0
	ds_read_b128 v[134:137], v0 offset:1024
	ds_read_b128 v[154:157], v0 offset:2048
	ds_read_b128 v[158:161], v0 offset:3072
	s_cmp_eq_u32 s17, 28
	s_cselect_b32 s9, s0, s7
	s_cselect_b32 s8, s1, s6
	s_cselect_b32 s7, s12, s15
	s_cselect_b32 s6, s13, s14
	v_lshl_add_u64 v[212:213], s[4:5], 0, v[150:151]
	s_add_i32 m0, s30, 0xc000
	ds_read_b128 v[184:187], v149
	ds_read_b128 v[188:191], v149 offset:1024
	ds_read_b128 v[192:195], v149 offset:2048
	ds_read_b128 v[196:199], v149 offset:3072
	ds_read_b128 v[200:203], v149 offset:4096
	ds_read_b128 v[204:207], v149 offset:5120
	ds_read_b128 v[208:211], v149 offset:6144
	ds_read_b128 v[224:227], v149 offset:7168
	global_load_lds_dwordx4 v[212:213], off
	v_lshl_add_u64 v[212:213], s[4:5], 0, v[152:153]
	s_add_i32 m0, s30, 0xe000
	s_nop 0
	global_load_lds_dwordx4 v[212:213], off
	s_waitcnt lgkmcnt(8)
	s_barrier
	s_waitcnt lgkmcnt(0)
	s_setprio 1
	s_waitcnt lgkmcnt(0)
	v_mfma_f32_16x16x32_bf16 v[122:125], v[130:133], v[184:187], v[122:125]
	v_mfma_f32_16x16x32_bf16 v[126:129], v[154:157], v[184:187], v[126:129]
	v_mfma_f32_16x16x32_bf16 v[110:113], v[130:133], v[192:195], v[110:113]
	v_mfma_f32_16x16x32_bf16 v[106:109], v[154:157], v[192:195], v[106:109]
	v_mfma_f32_16x16x32_bf16 v[94:97], v[130:133], v[200:203], v[94:97]
	v_mfma_f32_16x16x32_bf16 v[90:93], v[154:157], v[200:203], v[90:93]
	v_mfma_f32_16x16x32_bf16 v[78:81], v[130:133], v[208:211], v[78:81]
	v_mfma_f32_16x16x32_bf16 v[74:77], v[154:157], v[208:211], v[74:77]
	v_mfma_f32_16x16x32_bf16 v[122:125], v[134:137], v[188:191], v[122:125]
	v_mfma_f32_16x16x32_bf16 v[126:129], v[158:161], v[188:191], v[126:129]
	v_mfma_f32_16x16x32_bf16 v[110:113], v[134:137], v[196:199], v[110:113]
	v_mfma_f32_16x16x32_bf16 v[106:109], v[158:161], v[196:199], v[106:109]
	v_mfma_f32_16x16x32_bf16 v[94:97], v[134:137], v[204:207], v[94:97]
	v_mfma_f32_16x16x32_bf16 v[90:93], v[158:161], v[204:207], v[90:93]
	v_mfma_f32_16x16x32_bf16 v[78:81], v[134:137], v[224:227], v[78:81]
	v_mfma_f32_16x16x32_bf16 v[74:77], v[158:161], v[224:227], v[74:77]
	s_setprio 0
	s_barrier
	s_add_i32 s26, 0, 0x14000
	s_add_i32 s19, s19, s29
	v_add_u32_e32 v0, s26, v145
	v_lshl_add_u64 v[212:213], s[6:7], 0, v[140:141]
	s_mov_b32 m0, s19
	ds_read_b128 v[228:231], v0
	ds_read_b128 v[232:235], v0 offset:1024
	ds_read_b128 v[236:239], v0 offset:2048
	ds_read_b128 v[240:243], v0 offset:3072
	global_load_lds_dwordx4 v[212:213], off
	v_lshl_add_u64 v[214:215], s[6:7], 0, v[138:139]
	s_add_i32 m0, s19, 0x2000
	s_nop 0
	global_load_lds_dwordx4 v[214:215], off
	s_barrier
	s_waitcnt lgkmcnt(0)
	s_setprio 1
	s_waitcnt lgkmcnt(0)
	v_mfma_f32_16x16x32_bf16 v[118:121], v[228:231], v[184:187], v[118:121]
	v_mfma_f32_16x16x32_bf16 v[114:117], v[236:239], v[184:187], v[114:117]
	v_mfma_f32_16x16x32_bf16 v[102:105], v[228:231], v[192:195], v[102:105]
	v_mfma_f32_16x16x32_bf16 v[98:101], v[236:239], v[192:195], v[98:101]
	v_mfma_f32_16x16x32_bf16 v[86:89], v[228:231], v[200:203], v[86:89]
	v_mfma_f32_16x16x32_bf16 v[82:85], v[236:239], v[200:203], v[82:85]
	v_mfma_f32_16x16x32_bf16 v[70:73], v[228:231], v[208:211], v[70:73]
	v_mfma_f32_16x16x32_bf16 v[66:69], v[236:239], v[208:211], v[66:69]
	v_mfma_f32_16x16x32_bf16 v[118:121], v[232:235], v[188:191], v[118:121]
	v_mfma_f32_16x16x32_bf16 v[114:117], v[240:243], v[188:191], v[114:117]
	v_mfma_f32_16x16x32_bf16 v[102:105], v[232:235], v[196:199], v[102:105]
	v_mfma_f32_16x16x32_bf16 v[98:101], v[240:243], v[196:199], v[98:101]
	v_mfma_f32_16x16x32_bf16 v[86:89], v[232:235], v[204:207], v[86:89]
	v_mfma_f32_16x16x32_bf16 v[82:85], v[240:243], v[204:207], v[82:85]
	v_mfma_f32_16x16x32_bf16 v[70:73], v[232:235], v[224:227], v[70:73]
	v_mfma_f32_16x16x32_bf16 v[66:69], v[240:243], v[224:227], v[66:69]
	s_setprio 0
	s_mov_b32 m0, s30
	v_lshl_add_u64 v[218:219], s[8:9], 0, v[140:141]
	s_barrier
	ds_read_b128 v[184:187], v149 offset:16384
	ds_read_b128 v[188:191], v149 offset:17408
	ds_read_b128 v[192:195], v149 offset:18432
	ds_read_b128 v[196:199], v149 offset:19456
	ds_read_b128 v[200:203], v149 offset:20480
	ds_read_b128 v[204:207], v149 offset:21504
	ds_read_b128 v[208:211], v149 offset:22528
	ds_read_b128 v[224:227], v149 offset:23552
	global_load_lds_dwordx4 v[218:219], off
	v_lshl_add_u64 v[244:245], s[8:9], 0, v[138:139]
	s_mov_b32 m0, s31
	s_nop 0
	global_load_lds_dwordx4 v[244:245], off
	s_barrier
	s_waitcnt lgkmcnt(0)
	s_setprio 1
	s_waitcnt lgkmcnt(0)
	v_mfma_f32_16x16x32_bf16 v[62:65], v[130:133], v[184:187], v[62:65]
	v_mfma_f32_16x16x32_bf16 v[58:61], v[154:157], v[184:187], v[58:61]
	v_mfma_f32_16x16x32_bf16 v[46:49], v[130:133], v[192:195], v[46:49]
	v_mfma_f32_16x16x32_bf16 v[42:45], v[154:157], v[192:195], v[42:45]
	v_mfma_f32_16x16x32_bf16 v[30:33], v[130:133], v[200:203], v[30:33]
	v_mfma_f32_16x16x32_bf16 v[26:29], v[154:157], v[200:203], v[26:29]
	v_mfma_f32_16x16x32_bf16 v[14:17], v[130:133], v[208:211], v[14:17]
	v_mfma_f32_16x16x32_bf16 v[10:13], v[154:157], v[208:211], v[10:13]
	v_mfma_f32_16x16x32_bf16 v[62:65], v[134:137], v[188:191], v[62:65]
	v_mfma_f32_16x16x32_bf16 v[58:61], v[158:161], v[188:191], v[58:61]
	v_mfma_f32_16x16x32_bf16 v[46:49], v[134:137], v[196:199], v[46:49]
	v_mfma_f32_16x16x32_bf16 v[42:45], v[158:161], v[196:199], v[42:45]
	v_mfma_f32_16x16x32_bf16 v[30:33], v[134:137], v[204:207], v[30:33]
	v_mfma_f32_16x16x32_bf16 v[26:29], v[158:161], v[204:207], v[26:29]
	v_mfma_f32_16x16x32_bf16 v[14:17], v[134:137], v[224:227], v[14:17]
	v_mfma_f32_16x16x32_bf16 v[10:13], v[158:161], v[224:227], v[10:13]
	s_setprio 0
	s_barrier
; #define PG8_STAGE(bufoff, gbase, voff) do { _Pragma("unroll") for (int _i = 0; _i < 2; ++_i) \
;         __builtin_amdgcn_global_load_lds((const unsigned*)((const char*)(gbase) + (voff)[_i]), (LAS unsigned*)(lds + (bufoff) + ldsw + _i * 8192), 16, 0, 0); } while (0)
; #define PG8_LDA(dst, b, h) do { _Pragma("unroll") for (int m = 0; m < 4; ++m) _Pragma("unroll") for (int k = 0; k < 2; ++k) dst[m][k] = *(const LAS bf16x8*)(lds + PG8_SA(b, h) + aoff + m * 2048 + k * 1024); } while (0)
; #define PG8_LDB(dst, b, h) do { _Pragma("unroll") for (int n = 0; n < 2; ++n) _Pragma("unroll") for (int k = 0; k < 2; ++k) dst[n][k] = *(const LAS bf16x8*)(lds + PG8_SB(b, h) + boff + n * 2048 + k * 1024); } while (0)
; #define PG8_MMA(ai, bj, At, Bt) do { __builtin_amdgcn_s_setprio(1); _Pragma("unroll") for (int m = 0; m < 4; ++m) _Pragma("unroll") for (int n = 0; n < 2; ++n) _Pragma("unroll") for (int k = 0; k < 2; ++k) \
;         acc[ai][bj][m][n] = __builtin_amdgcn_mfma_f32_16x16x32_bf16(Bt[n][k], At[m][k], acc[ai][bj][m][n], 0, 0, 0); __builtin_amdgcn_s_setprio(0); } while (0)
; #define PG8_WAIT_V(n) asm volatile("s_waitcnt vmcnt(" #n ")" ::: "memory")
; #define PG8_WAIT_L(n) asm volatile("s_waitcnt lgkmcnt(" #n ")" ::: "memory")
; #define PG8_BAR __builtin_amdgcn_s_barrier()
; #define PG8_SCHED __builtin_amdgcn_sched_barrier(0)
; template <class Epi>
; __device__ __forceinline__ void gemm_phase(LAS unsigned char* lds, const Gemm g, const Order& S, KP kp, int code, int wv) {
;     ...
;             PG8_STAGE(PG8_SB(0, 1), b2 + hstepB, voffB);
;             PG8_WAIT_V(6); PG8_BAR; PG8_MMA(1, 1, At, B1); PG8_BAR;
;             PG8_LDB(B0, 1, 0); PG8_SCHED; PG8_LDA(At, 1, 0); PG8_STAGE(PG8_SA(0, 1), a2 + hstepA, voffA);
;             PG8_WAIT_L(8); PG8_BAR; PG8_WAIT_L(0); PG8_MMA(0, 0, At, B0); PG8_BAR; PG8_SCHED;
;             PG8_LDB(B1, 1, 1); PG8_STAGE(PG8_SB(1, 0), b3, voffB);
;             PG8_BAR; PG8_WAIT_L(0); PG8_MMA(0, 1, At, B1); PG8_BAR;
;             PG8_LDA(At, 1, 1); PG8_STAGE(PG8_SA(1, 0), a3, voffA);
;             PG8_BAR; PG8_WAIT_L(0); PG8_MMA(1, 0, At, B0); PG8_BAR; PG8_SCHED;
;             PG8_STAGE(PG8_SB(1, 1), b3 + hstepB, voffB);
;             PG8_WAIT_V(6); PG8_BAR; PG8_MMA(1, 1, At, B1); PG8_BAR;
	s_add_u32 s24, s6, 0x80000
	s_addc_u32 s25, s7, 0
	s_add_i32 s19, s26, s29
	v_lshl_add_u64 v[130:131], s[24:25], 0, v[140:141]
	s_mov_b32 m0, s19
	s_nop 0
	global_load_lds_dwordx4 v[130:131], off
	v_lshl_add_u64 v[130:131], s[24:25], 0, v[138:139]
	s_add_i32 m0, s19, 0x2000
	s_nop 0
	global_load_lds_dwordx4 v[130:131], off
	s_waitcnt vmcnt(6)
	s_barrier
	s_setprio 1
	v_mfma_f32_16x16x32_bf16 v[54:57], v[228:231], v[184:187], v[54:57]
	v_mfma_f32_16x16x32_bf16 v[50:53], v[236:239], v[184:187], v[50:53]
	v_mfma_f32_16x16x32_bf16 v[38:41], v[228:231], v[192:195], v[38:41]
	v_mfma_f32_16x16x32_bf16 v[34:37], v[236:239], v[192:195], v[34:37]
	v_mfma_f32_16x16x32_bf16 v[22:25], v[228:231], v[200:203], v[22:25]
	v_mfma_f32_16x16x32_bf16 v[18:21], v[236:239], v[200:203], v[18:21]
	v_mfma_f32_16x16x32_bf16 v[6:9], v[228:231], v[208:211], v[6:9]
	v_mfma_f32_16x16x32_bf16 v[2:5], v[236:239], v[208:211], v[2:5]
	v_mfma_f32_16x16x32_bf16 v[54:57], v[232:235], v[188:191], v[54:57]
	v_mfma_f32_16x16x32_bf16 v[50:53], v[240:243], v[188:191], v[50:53]
	v_mfma_f32_16x16x32_bf16 v[38:41], v[232:235], v[196:199], v[38:41]
	v_mfma_f32_16x16x32_bf16 v[34:37], v[240:243], v[196:199], v[34:37]
	v_mfma_f32_16x16x32_bf16 v[22:25], v[232:235], v[204:207], v[22:25]
	v_mfma_f32_16x16x32_bf16 v[18:21], v[240:243], v[204:207], v[18:21]
	v_mfma_f32_16x16x32_bf16 v[6:9], v[232:235], v[224:227], v[6:9]
	v_mfma_f32_16x16x32_bf16 v[2:5], v[240:243], v[224:227], v[2:5]
	s_setprio 0
	s_add_i32 s19, 0, 0x18000
	v_add_u32_e32 v0, s19, v145
	s_barrier
	ds_read_b128 v[130:133], v0
	ds_read_b128 v[134:137], v0 offset:1024
	ds_read_b128 v[154:157], v0 offset:2048
	ds_read_b128 v[158:161], v0 offset:3072
	s_add_u32 s8, s8, 0x80000
	s_addc_u32 s9, s9, 0
	s_mov_b32 m0, s34
	v_lshl_add_u64 v[228:229], s[8:9], 0, v[140:141]
	ds_read_b128 v[184:187], v149 offset:32768
	ds_read_b128 v[188:191], v149 offset:33792
	ds_read_b128 v[192:195], v149 offset:34816
	ds_read_b128 v[196:199], v149 offset:35840
	ds_read_b128 v[200:203], v149 offset:36864
	ds_read_b128 v[204:207], v149 offset:37888
	ds_read_b128 v[208:211], v149 offset:38912
	ds_read_b128 v[224:227], v149 offset:39936
	global_load_lds_dwordx4 v[228:229], off
	v_lshl_add_u64 v[228:229], s[8:9], 0, v[138:139]
	s_mov_b32 m0, s35
	s_nop 0
	global_load_lds_dwordx4 v[228:229], off
	s_waitcnt lgkmcnt(8)
	s_barrier
	s_waitcnt lgkmcnt(0)
	s_setprio 1
	s_waitcnt lgkmcnt(0)
	v_mfma_f32_16x16x32_bf16 v[122:125], v[130:133], v[184:187], v[122:125]
	v_mfma_f32_16x16x32_bf16 v[126:129], v[154:157], v[184:187], v[126:129]
	v_mfma_f32_16x16x32_bf16 v[110:113], v[130:133], v[192:195], v[110:113]
	v_mfma_f32_16x16x32_bf16 v[106:109], v[154:157], v[192:195], v[106:109]
	v_mfma_f32_16x16x32_bf16 v[94:97], v[130:133], v[200:203], v[94:97]
	v_mfma_f32_16x16x32_bf16 v[90:93], v[154:157], v[200:203], v[90:93]
	v_mfma_f32_16x16x32_bf16 v[78:81], v[130:133], v[208:211], v[78:81]
	v_mfma_f32_16x16x32_bf16 v[74:77], v[154:157], v[208:211], v[74:77]
	v_mfma_f32_16x16x32_bf16 v[122:125], v[134:137], v[188:191], v[122:125]
	v_mfma_f32_16x16x32_bf16 v[126:129], v[158:161], v[188:191], v[126:129]
	v_mfma_f32_16x16x32_bf16 v[110:113], v[134:137], v[196:199], v[110:113]
	v_mfma_f32_16x16x32_bf16 v[106:109], v[158:161], v[196:199], v[106:109]
	v_mfma_f32_16x16x32_bf16 v[94:97], v[134:137], v[204:207], v[94:97]
	v_mfma_f32_16x16x32_bf16 v[90:93], v[158:161], v[204:207], v[90:93]
	v_mfma_f32_16x16x32_bf16 v[78:81], v[134:137], v[224:227], v[78:81]
	v_mfma_f32_16x16x32_bf16 v[74:77], v[158:161], v[224:227], v[74:77]
	s_setprio 0
	s_barrier
	s_add_i32 s8, 0, 0x1c000
	s_add_i32 s9, s19, s29
	v_add_u32_e32 v0, s8, v145
	v_lshl_add_u64 v[212:213], v[212:213], 0, s[70:71]
	s_mov_b32 m0, s9
	ds_read_b128 v[228:231], v0
	ds_read_b128 v[232:235], v0 offset:1024
	ds_read_b128 v[236:239], v0 offset:2048
	ds_read_b128 v[240:243], v0 offset:3072
	global_load_lds_dwordx4 v[212:213], off
	v_lshl_add_u64 v[212:213], v[214:215], 0, s[70:71]
	s_add_i32 m0, s9, 0x2000
	s_nop 0
	global_load_lds_dwordx4 v[212:213], off
	s_barrier
	s_waitcnt lgkmcnt(0)
	s_setprio 1
	s_waitcnt lgkmcnt(0)
	v_mfma_f32_16x16x32_bf16 v[118:121], v[228:231], v[184:187], v[118:121]
	v_mfma_f32_16x16x32_bf16 v[114:117], v[236:239], v[184:187], v[114:117]
	v_mfma_f32_16x16x32_bf16 v[102:105], v[228:231], v[192:195], v[102:105]
	v_mfma_f32_16x16x32_bf16 v[98:101], v[236:239], v[192:195], v[98:101]
	v_mfma_f32_16x16x32_bf16 v[86:89], v[228:231], v[200:203], v[86:89]
	v_mfma_f32_16x16x32_bf16 v[82:85], v[236:239], v[200:203], v[82:85]
	v_mfma_f32_16x16x32_bf16 v[70:73], v[228:231], v[208:211], v[70:73]
	v_mfma_f32_16x16x32_bf16 v[66:69], v[236:239], v[208:211], v[66:69]
	v_mfma_f32_16x16x32_bf16 v[118:121], v[232:235], v[188:191], v[118:121]
	v_mfma_f32_16x16x32_bf16 v[114:117], v[240:243], v[188:191], v[114:117]
	v_mfma_f32_16x16x32_bf16 v[102:105], v[232:235], v[196:199], v[102:105]
	v_mfma_f32_16x16x32_bf16 v[98:101], v[240:243], v[196:199], v[98:101]
	v_mfma_f32_16x16x32_bf16 v[86:89], v[232:235], v[204:207], v[86:89]
	v_mfma_f32_16x16x32_bf16 v[82:85], v[240:243], v[204:207], v[82:85]
	v_mfma_f32_16x16x32_bf16 v[70:73], v[232:235], v[224:227], v[70:73]
	v_mfma_f32_16x16x32_bf16 v[66:69], v[240:243], v[224:227], v[66:69]
	s_setprio 0
	s_mov_b32 m0, s36
	v_lshl_add_u64 v[212:213], v[218:219], 0, s[70:71]
	s_barrier
	ds_read_b128 v[184:187], v149 offset:49152
	ds_read_b128 v[188:191], v149 offset:50176
	ds_read_b128 v[192:195], v149 offset:51200
	ds_read_b128 v[196:199], v149 offset:52224
	ds_read_b128 v[200:203], v149 offset:53248
	ds_read_b128 v[204:207], v149 offset:54272
	ds_read_b128 v[208:211], v149 offset:55296
	ds_read_b128 v[224:227], v149 offset:56320
	global_load_lds_dwordx4 v[212:213], off
	v_lshl_add_u64 v[212:213], v[244:245], 0, s[70:71]
	s_mov_b32 m0, s37
	s_nop 0
	global_load_lds_dwordx4 v[212:213], off
	s_barrier
; #define PG8_STAGE(bufoff, gbase, voff) do { _Pragma("unroll") for (int _i = 0; _i < 2; ++_i) \
;         __builtin_amdgcn_global_load_lds((const unsigned*)((const char*)(gbase) + (voff)[_i]), (LAS unsigned*)(lds + (bufoff) + ldsw + _i * 8192), 16, 0, 0); } while (0)
; #define PG8_MMA(ai, bj, At, Bt) do { __builtin_amdgcn_s_setprio(1); _Pragma("unroll") for (int m = 0; m < 4; ++m) _Pragma("unroll") for (int n = 0; n < 2; ++n) _Pragma("unroll") for (int k = 0; k < 2; ++k) \
;         acc[ai][bj][m][n] = __builtin_amdgcn_mfma_f32_16x16x32_bf16(Bt[n][k], At[m][k], acc[ai][bj][m][n], 0, 0, 0); __builtin_amdgcn_s_setprio(0); } while (0)
; #define PG8_WAIT_V(n) asm volatile("s_waitcnt vmcnt(" #n ")" ::: "memory")
; #define PG8_WAIT_L(n) asm volatile("s_waitcnt lgkmcnt(" #n ")" ::: "memory")
; #define PG8_BAR __builtin_amdgcn_s_barrier()
; #define PG8_SCHED __builtin_amdgcn_sched_barrier(0)
;     __device__ __forceinline__ void operator()(const f32x4 (&acc)[2][2][4][2], const Unit& u, int wr, int wc, int fr, int fq) const {
;         const int pm = u.pm, pn = u.pn;
;         const bool ctx = pm >= 32;
;         const int rbase = pm * BM + wr * 64 + fr;
;         const int b = ctx ? pm - 32 : (pm >> 3);
;         const int ccb = ctx ? 0 : 2 + 2 * (pm & 7);
;         if (pn < 8) {
;             const bool isk = pn >= 4;
;             const int d0 = 16 * wc + 4 * fq;
; template <class Epi>
; __device__ __forceinline__ void gemm_phase(LAS unsigned char* lds, const Gemm g, const Order& S, KP kp, int code, int wv) {
;     ...
;             PG8_BAR; PG8_WAIT_L(0); PG8_MMA(1, 0, At, B0); PG8_BAR; PG8_SCHED;
;             PG8_STAGE(PG8_SB(1, 1), b3 + hstepB, voffB);
;             PG8_WAIT_V(6); PG8_BAR; PG8_MMA(1, 1, At, B1); PG8_BAR;
;         }
;         if (!Epi::HAS_FUSED || (code & 8)) { KP kq = kp; asm volatile("" : "+s"(kq)); const Epi E = Epi::make(kq, code); E(acc, cur, wr, wc, fr, fq); }
	s_waitcnt lgkmcnt(0)
	s_setprio 1
	s_waitcnt lgkmcnt(0)
	v_mfma_f32_16x16x32_bf16 v[62:65], v[130:133], v[184:187], v[62:65]
	v_mfma_f32_16x16x32_bf16 v[58:61], v[154:157], v[184:187], v[58:61]
	v_mfma_f32_16x16x32_bf16 v[46:49], v[130:133], v[192:195], v[46:49]
	v_mfma_f32_16x16x32_bf16 v[42:45], v[154:157], v[192:195], v[42:45]
	v_mfma_f32_16x16x32_bf16 v[30:33], v[130:133], v[200:203], v[30:33]
	v_mfma_f32_16x16x32_bf16 v[26:29], v[154:157], v[200:203], v[26:29]
	v_mfma_f32_16x16x32_bf16 v[14:17], v[130:133], v[208:211], v[14:17]
	v_mfma_f32_16x16x32_bf16 v[10:13], v[154:157], v[208:211], v[10:13]
	v_mfma_f32_16x16x32_bf16 v[62:65], v[134:137], v[188:191], v[62:65]
	v_mfma_f32_16x16x32_bf16 v[58:61], v[158:161], v[188:191], v[58:61]
	v_mfma_f32_16x16x32_bf16 v[46:49], v[134:137], v[196:199], v[46:49]
	v_mfma_f32_16x16x32_bf16 v[42:45], v[158:161], v[196:199], v[42:45]
	v_mfma_f32_16x16x32_bf16 v[30:33], v[134:137], v[204:207], v[30:33]
	v_mfma_f32_16x16x32_bf16 v[26:29], v[158:161], v[204:207], v[26:29]
	v_mfma_f32_16x16x32_bf16 v[14:17], v[134:137], v[224:227], v[14:17]
	v_mfma_f32_16x16x32_bf16 v[10:13], v[158:161], v[224:227], v[10:13]
	s_setprio 0
	s_barrier
	s_add_u32 s6, s6, 0x80080
	s_addc_u32 s7, s7, 0
	s_add_i32 s8, s8, s29
	v_lshl_add_u64 v[130:131], s[6:7], 0, v[140:141]
	s_mov_b32 m0, s8
	s_nop 0
	global_load_lds_dwordx4 v[130:131], off
	v_lshl_add_u64 v[130:131], s[6:7], 0, v[138:139]
	s_add_i32 m0, s8, 0x2000
	s_nop 0
	global_load_lds_dwordx4 v[130:131], off
	s_waitcnt vmcnt(6)
	s_barrier
	s_setprio 1
	v_mfma_f32_16x16x32_bf16 v[54:57], v[228:231], v[184:187], v[54:57]
	v_mfma_f32_16x16x32_bf16 v[50:53], v[236:239], v[184:187], v[50:53]
	v_mfma_f32_16x16x32_bf16 v[38:41], v[228:231], v[192:195], v[38:41]
	v_mfma_f32_16x16x32_bf16 v[34:37], v[236:239], v[192:195], v[34:37]
	v_mfma_f32_16x16x32_bf16 v[22:25], v[228:231], v[200:203], v[22:25]
	v_mfma_f32_16x16x32_bf16 v[18:21], v[236:239], v[200:203], v[18:21]
	v_mfma_f32_16x16x32_bf16 v[6:9], v[228:231], v[208:211], v[6:9]
	v_mfma_f32_16x16x32_bf16 v[2:5], v[236:239], v[208:211], v[2:5]
	v_mfma_f32_16x16x32_bf16 v[54:57], v[232:235], v[188:191], v[54:57]
	v_mfma_f32_16x16x32_bf16 v[50:53], v[240:243], v[188:191], v[50:53]
	v_mfma_f32_16x16x32_bf16 v[38:41], v[232:235], v[196:199], v[38:41]
	v_mfma_f32_16x16x32_bf16 v[34:37], v[240:243], v[196:199], v[34:37]
	v_mfma_f32_16x16x32_bf16 v[22:25], v[232:235], v[204:207], v[22:25]
	v_mfma_f32_16x16x32_bf16 v[18:21], v[240:243], v[204:207], v[18:21]
	v_mfma_f32_16x16x32_bf16 v[6:9], v[232:235], v[224:227], v[6:9]
	v_mfma_f32_16x16x32_bf16 v[2:5], v[240:243], v[224:227], v[2:5]
	s_setprio 0
	s_add_i32 s17, s17, 2
	s_add_u32 s4, s4, 0x100
	s_addc_u32 s5, s5, 0
	s_add_u32 s14, s14, 0x100
	s_addc_u32 s15, s15, 0
	s_cmp_gt_u32 s17, 29
	s_barrier
	s_cbranch_scc0 .LBB0_136
	v_mbcnt_lo_u32_b32 v174, -1, 0
	v_mbcnt_hi_u32_b32 v174, -1, v174
	v_bfe_u32 v175, v174, 4, 1
	v_mul_u32_u24_e32 v174, 0x88, v175
	v_sub_u32_e32 v174, 0x80, v174
	v_sub_u32_e32 v175, 0, v175
	v_mbcnt_lo_u32_b32 v180, -1, 0
	v_mbcnt_hi_u32_b32 v180, -1, v180
	v_bfe_u32 v180, v180, 4, 1
	v_mul_u32_u24_e32 v180, 24, v180
	v_mov_b32_e32 v181, 0
	v_mbcnt_lo_u32_b32 v164, -1, 0
	v_mbcnt_hi_u32_b32 v164, -1, v164
	v_and_b32_e32 v166, 3, v164
	v_mul_u32_u24_e32 v166, 0xfe, v166
	v_mov_b32_e32 v167, 0
	v_and_b32_e32 v164, 1, v164
	v_cmp_eq_u32_e64 s[98:99], 0, v164
	v_mov_b32_e32 v165, 0x3020706
	v_mov_b32_e32 v170, 0x5040100
	s_nop 1
	v_cndmask_b32_e64 v165, v165, v170, s[98:99]
	s_mov_b32 s98, 0xcccccccc
	s_mov_b32 s99, 0xcccccccc
	s_mov_b64 s[0:1], s[78:79]
	s_cmp_lt_i32 s10, 32
	s_load_dwordx2 s[24:25], s[0:1], 0xc0
	s_cselect_b64 s[6:7], -1, 0
	s_lshl_b32 s4, s10, 1
	s_and_b32 s4, s4, 14
	s_sub_i32 s0, s10, 32
	s_ashr_i32 s1, s10, 3
	s_add_i32 s4, s4, 2
	s_cmp_gt_i32 s10, 31
	v_lshl_add_u32 v154, s10, 8, v142
	s_cselect_b32 s8, s0, s1
	s_cselect_b32 s10, 0, s4
	s_cmp_gt_i32 s11, 7
	s_mov_b64 s[0:1], -1
	s_cbranch_scc0 .LBB0_143
	s_cmp_gt_u32 s11, 11
	s_cbranch_scc0 .LBB0_140
; __device__ __forceinline__ unsigned cvt_pk_bf16(float lo, float hi) { unsigned r; asm("v_cvt_pk_bf16_f32 %0, %1, %2" : "=v"(r) : "v"(lo), "v"(hi)); return r; }
;     __device__ __forceinline__ void operator()(const f32x4 (&acc)[2][2][4][2], const Unit& u, int wr, int wc, int fr, int fq) const {
;     ...
;         } else {
;             const int col0 = (pn - 12) * BM + wc * 32 + 4 * fq;
; #pragma unroll
;             for (int ai = 0; ai < 2; ++ai)
; #pragma unroll
;                 for (int m = 0; m < 4; ++m) {
;                     bf16_t* rowp = pr + (size_t)(rbase + ai * HALF + m * 16) * 4096 + col0;
; #pragma unroll
;                     for (int bj = 0; bj < 2; ++bj)
; #pragma unroll
;                         for (int n = 0; n < 2; ++n) {
;                             const f32x4 x = acc[ai][bj][m][n];
;                             u32x2 w; w.x = cvt_pk_bf16(x[0], x[1]); w.y = cvt_pk_bf16(x[2], x[3]);
;                             *(u32x2*)(rowp + bj * HALF + n * 16) = w;
;                         }
;                 }
	s_waitcnt lgkmcnt(0)
	s_add_u32 s4, s24, 0x242b4000
	v_ashrrev_i32_e32 v155, 31, v154
	s_addc_u32 s5, s25, 0
	v_lshl_add_u32 v0, s11, 8, v147
	v_lshlrev_b64 v[130:131], 13, v[154:155]
	v_lshl_add_u64 v[130:131], s[4:5], 0, v[130:131]
	v_lshlrev_b64 v[132:133], 1, v[0:1]
	v_lshl_add_u64 v[130:131], v[130:131], 0, v[132:133]
	v_cvt_pk_bf16_f32 v168, v122, v123
	v_cvt_pk_bf16_f32 v169, v124, v125
	v_cvt_pk_bf16_f32 v170, v126, v127
	v_cvt_pk_bf16_f32 v171, v128, v129
	v_lshl_add_u64 v[176:177], v[130:131], 0, v[180:181]
	s_nop 0
	v_permlane16_swap_b32_e32 v168, v170
	v_permlane16_swap_b32_e32 v169, v171
	global_store_dwordx4 v[176:177], v[168:171], off
	v_cvt_pk_bf16_f32 v172, v118, v119
	v_cvt_pk_bf16_f32 v173, v120, v121
	v_cvt_pk_bf16_f32 v174, v114, v115
	v_cvt_pk_bf16_f32 v175, v116, v117
	v_lshl_add_u64 v[176:177], v[130:131], 0, v[180:181]
	s_nop 0
	v_permlane16_swap_b32_e32 v172, v174
	v_permlane16_swap_b32_e32 v173, v175
	global_store_dwordx4 v[176:177], v[172:175], off offset:256
	v_or_b32_e32 v134, 16, v154
	v_ashrrev_i32_e32 v135, 31, v134
	v_lshlrev_b64 v[134:135], 13, v[134:135]
	v_lshl_add_u64 v[134:135], s[4:5], 0, v[134:135]
	v_lshl_add_u64 v[134:135], v[134:135], 0, v[132:133]
	v_cvt_pk_bf16_f32 v168, v110, v111
	v_cvt_pk_bf16_f32 v169, v112, v113
	v_cvt_pk_bf16_f32 v170, v106, v107
	v_cvt_pk_bf16_f32 v171, v108, v109
	v_lshl_add_u64 v[176:177], v[134:135], 0, v[180:181]
	s_nop 0
	v_permlane16_swap_b32_e32 v168, v170
	v_permlane16_swap_b32_e32 v169, v171
	global_store_dwordx4 v[176:177], v[168:171], off
	v_cvt_pk_bf16_f32 v172, v102, v103
	v_cvt_pk_bf16_f32 v173, v104, v105
	v_cvt_pk_bf16_f32 v174, v98, v99
	v_cvt_pk_bf16_f32 v175, v100, v101
	v_lshl_add_u64 v[176:177], v[134:135], 0, v[180:181]
	s_nop 0
	v_permlane16_swap_b32_e32 v172, v174
	v_permlane16_swap_b32_e32 v173, v175
	global_store_dwordx4 v[176:177], v[172:175], off offset:256
	v_or_b32_e32 v134, 32, v154
	v_ashrrev_i32_e32 v135, 31, v134
	v_lshlrev_b64 v[134:135], 13, v[134:135]
	v_lshl_add_u64 v[134:135], s[4:5], 0, v[134:135]
	v_lshl_add_u64 v[134:135], v[134:135], 0, v[132:133]
	v_cvt_pk_bf16_f32 v168, v94, v95
	v_cvt_pk_bf16_f32 v169, v96, v97
	v_cvt_pk_bf16_f32 v170, v90, v91
	v_cvt_pk_bf16_f32 v171, v92, v93
	v_lshl_add_u64 v[176:177], v[134:135], 0, v[180:181]
	s_nop 0
	v_permlane16_swap_b32_e32 v168, v170
	v_permlane16_swap_b32_e32 v169, v171
	global_store_dwordx4 v[176:177], v[168:171], off
	v_cvt_pk_bf16_f32 v172, v86, v87
	v_cvt_pk_bf16_f32 v173, v88, v89
	v_cvt_pk_bf16_f32 v174, v82, v83
	v_cvt_pk_bf16_f32 v175, v84, v85
	v_lshl_add_u64 v[176:177], v[134:135], 0, v[180:181]
	s_nop 0
	v_permlane16_swap_b32_e32 v172, v174
	v_permlane16_swap_b32_e32 v173, v175
	global_store_dwordx4 v[176:177], v[172:175], off offset:256
	v_or_b32_e32 v134, 48, v154
	v_ashrrev_i32_e32 v135, 31, v134
	v_lshlrev_b64 v[134:135], 13, v[134:135]
	v_lshl_add_u64 v[134:135], s[4:5], 0, v[134:135]
	v_lshl_add_u64 v[132:133], v[134:135], 0, v[132:133]
	v_cvt_pk_bf16_f32 v168, v78, v79
	v_cvt_pk_bf16_f32 v169, v80, v81
	v_cvt_pk_bf16_f32 v170, v74, v75
	v_cvt_pk_bf16_f32 v171, v76, v77
	v_lshl_add_u64 v[176:177], v[132:133], 0, v[180:181]
	s_nop 0
	v_permlane16_swap_b32_e32 v168, v170
	v_permlane16_swap_b32_e32 v169, v171
	global_store_dwordx4 v[176:177], v[168:171], off
	s_mov_b64 s[0:1], 0x100000
	v_cvt_pk_bf16_f32 v172, v70, v71
	v_cvt_pk_bf16_f32 v173, v72, v73
	v_cvt_pk_bf16_f32 v174, v66, v67
	v_cvt_pk_bf16_f32 v175, v68, v69
	v_lshl_add_u64 v[176:177], v[132:133], 0, v[180:181]
	s_nop 0
	v_permlane16_swap_b32_e32 v172, v174
	v_permlane16_swap_b32_e32 v173, v175
	global_store_dwordx4 v[176:177], v[172:175], off offset:256
	v_lshl_add_u64 v[132:133], v[130:131], 0, s[0:1]
	s_mov_b32 s0, 0x100000
	v_add_co_u32_e32 v136, vcc, s0, v130
	s_mov_b32 s0, 0x120000
	s_nop 0
	v_addc_co_u32_e32 v137, vcc, 0, v131, vcc
	v_cvt_pk_bf16_f32 v168, v62, v63
	v_cvt_pk_bf16_f32 v169, v64, v65
	v_cvt_pk_bf16_f32 v170, v58, v59
	v_cvt_pk_bf16_f32 v171, v60, v61
	v_lshl_add_u64 v[176:177], v[136:137], 0, v[180:181]
	s_nop 0
	v_permlane16_swap_b32_e32 v168, v170
	v_permlane16_swap_b32_e32 v169, v171
	global_store_dwordx4 v[176:177], v[168:171], off
	v_add_co_u32_e32 v136, vcc, s0, v130
	v_cvt_pk_bf16_f32 v172, v54, v55
	v_cvt_pk_bf16_f32 v173, v56, v57
	v_cvt_pk_bf16_f32 v174, v50, v51
	v_cvt_pk_bf16_f32 v175, v52, v53
	v_lshl_add_u64 v[176:177], v[132:133], 0, v[180:181]
	s_nop 0
	v_permlane16_swap_b32_e32 v172, v174
	v_permlane16_swap_b32_e32 v173, v175
	global_store_dwordx4 v[176:177], v[172:175], off offset:256
	s_nop 0
	v_addc_co_u32_e32 v137, vcc, 0, v131, vcc
	v_lshl_add_u64 v[132:133], v[130:131], 0, s[74:75]
	v_cvt_pk_bf16_f32 v168, v46, v47
	v_cvt_pk_bf16_f32 v169, v48, v49
	v_cvt_pk_bf16_f32 v170, v42, v43
	v_cvt_pk_bf16_f32 v171, v44, v45
	v_lshl_add_u64 v[176:177], v[136:137], 0, v[180:181]
	s_nop 0
	v_permlane16_swap_b32_e32 v168, v170
	v_permlane16_swap_b32_e32 v169, v171
	global_store_dwordx4 v[176:177], v[168:171], off
	s_mov_b64 s[0:1], 0x140000
	v_cvt_pk_bf16_f32 v172, v38, v39
	v_cvt_pk_bf16_f32 v173, v40, v41
	v_cvt_pk_bf16_f32 v174, v34, v35
	v_cvt_pk_bf16_f32 v175, v36, v37
	v_lshl_add_u64 v[176:177], v[132:133], 0, v[180:181]
	s_nop 0
	v_permlane16_swap_b32_e32 v172, v174
	v_permlane16_swap_b32_e32 v173, v175
	global_store_dwordx4 v[176:177], v[172:175], off offset:256
	v_lshl_add_u64 v[132:133], v[130:131], 0, s[0:1]
	s_mov_b32 s0, 0x140000
	v_add_co_u32_e32 v136, vcc, s0, v130
	s_mov_b64 s[0:1], 0x160000
	s_nop 0
	v_addc_co_u32_e32 v137, vcc, 0, v131, vcc
	v_cvt_pk_bf16_f32 v168, v30, v31
	v_cvt_pk_bf16_f32 v169, v32, v33
	v_cvt_pk_bf16_f32 v170, v26, v27
	v_cvt_pk_bf16_f32 v171, v28, v29
	v_lshl_add_u64 v[176:177], v[136:137], 0, v[180:181]
	s_nop 0
	v_permlane16_swap_b32_e32 v168, v170
	v_permlane16_swap_b32_e32 v169, v171
	global_store_dwordx4 v[176:177], v[168:171], off
	v_cvt_pk_bf16_f32 v172, v22, v23
	v_cvt_pk_bf16_f32 v173, v24, v25
	v_cvt_pk_bf16_f32 v174, v18, v19
	v_cvt_pk_bf16_f32 v175, v20, v21
	v_lshl_add_u64 v[176:177], v[132:133], 0, v[180:181]
	s_nop 0
	v_permlane16_swap_b32_e32 v172, v174
	v_permlane16_swap_b32_e32 v173, v175
	global_store_dwordx4 v[176:177], v[172:175], off offset:256
	v_lshl_add_u64 v[132:133], v[130:131], 0, s[0:1]
	s_mov_b32 s0, 0x160000
	v_add_co_u32_e32 v130, vcc, s0, v130
	s_mov_b64 s[0:1], 0
	s_nop 0
	v_addc_co_u32_e32 v131, vcc, 0, v131, vcc
	v_cvt_pk_bf16_f32 v168, v14, v15
	v_cvt_pk_bf16_f32 v169, v16, v17
	v_cvt_pk_bf16_f32 v170, v10, v11
	v_cvt_pk_bf16_f32 v171, v12, v13
	v_lshl_add_u64 v[176:177], v[130:131], 0, v[180:181]
	s_nop 0
	v_permlane16_swap_b32_e32 v168, v170
	v_permlane16_swap_b32_e32 v169, v171
	global_store_dwordx4 v[176:177], v[168:171], off
	v_cvt_pk_bf16_f32 v172, v6, v7
	v_cvt_pk_bf16_f32 v173, v8, v9
	v_cvt_pk_bf16_f32 v174, v2, v3
	v_cvt_pk_bf16_f32 v175, v4, v5
	v_lshl_add_u64 v[176:177], v[132:133], 0, v[180:181]
	s_nop 0
	v_permlane16_swap_b32_e32 v172, v174
	v_permlane16_swap_b32_e32 v173, v175
	global_store_dwordx4 v[176:177], v[172:175], off offset:256

; __device__ __forceinline__ unsigned cvt_pk_bf16(float lo, float hi) { unsigned r; asm("v_cvt_pk_bf16_f32 %0, %1, %2" : "=v"(r) : "v"(lo), "v"(hi)); return r; }
;     __device__ __forceinline__ void operator()(const f32x4 (&acc)[2][2][4][2], const Unit& u, int wr, int wc, int fr, int fq) const {
;     ...
;                     if (!ctx) { const int t = row & (SEQ - 1); cs = *(const f32x4*)(rope + t * 64 + d0); sn = *(const f32x4*)(rope + SEQ * 64 + t * 64 + d0); }
; #pragma unroll
;                     for (int bj = 0; bj < 2; ++bj) {
;                         const int head = 2 * (pn & 3) + bj;
;                         const f32x4 x1 = acc[ai][bj][m][0], x2 = acc[ai][bj][m][1];
;                         f32x4 o1 = x1 * cs - x2 * sn, o2 = x1 * sn + x2 * cs;
;                         if (isk) { o1 = o1 * KSCALE; o2 = o2 * KSCALE; }
;                         u32x2 w1, w2; w1.x = cvt_pk_bf16(o1[0], o1[1]); w1.y = cvt_pk_bf16(o1[2], o1[3]); w2.x = cvt_pk_bf16(o2[0], o2[1]); w2.y = cvt_pk_bf16(o2[2], o2[3]);
;                         if (!ctx) { bf16_t* dp = (isk ? k : q) + (size_t)row * 1024 + head * 128 + d0; *(u32x2*)dp = w1; *(u32x2*)(dp + 64) = w2; }
.LBB0_147:
	s_cmp_gt_i32 s11, 3
	s_cselect_b64 s[6:7], -1, 0
	s_lshl_b32 s0, s11, 1
	s_and_b32 s11, s0, 6
	s_waitcnt vmcnt(0)
	v_pk_mul_f32 v[160:161], v[128:129], v[136:137]
	v_pk_mul_f32 v[128:129], v[128:129], v[132:133]
	s_add_u32 s12, s24, 0x1feb4000
	v_pk_mul_f32 v[184:185], v[126:127], v[134:135]
	v_pk_fma_f32 v[160:161], v[124:125], v[132:133], v[160:161] neg_lo:[0,0,1] neg_hi:[0,0,1]
	v_pk_fma_f32 v[124:125], v[124:125], v[136:137], v[128:129]
	s_addc_u32 s13, s25, 0
	v_pk_fma_f32 v[184:185], v[122:123], v[130:131], v[184:185] neg_lo:[0,0,1] neg_hi:[0,0,1]
	v_pk_mul_f32 v[126:127], v[126:127], v[130:131]
	v_pk_mul_f32 v[188:189], v[124:125], s[76:77] op_sel_hi:[1,0]
	s_add_u32 s14, s24, 0x20eb4000
	v_ashrrev_i32_e32 v155, 31, v154
	v_pk_fma_f32 v[122:123], v[122:123], v[134:135], v[126:127]
	v_pk_mul_f32 v[126:127], v[184:185], s[76:77] op_sel_hi:[1,0]
	v_pk_mul_f32 v[128:129], v[160:161], s[76:77] op_sel_hi:[1,0]
	v_cndmask_b32_e64 v0, v124, v188, s[6:7]
	v_cndmask_b32_e64 v125, v125, v189, s[6:7]
	s_addc_u32 s15, s25, 0
	v_lshlrev_b64 v[158:159], 11, v[154:155]
	v_pk_mul_f32 v[186:187], v[122:123], s[76:77] op_sel_hi:[1,0]
	v_cndmask_b32_e64 v124, v160, v128, s[6:7]
	v_cndmask_b32_e64 v126, v184, v126, s[6:7]
	v_cndmask_b32_e64 v127, v185, v127, s[6:7]
	v_cvt_pk_bf16_f32 v125, v0, v125
	s_and_b64 vcc, exec, s[4:5]
	v_lshlrev_b32_e32 v0, 1, v146
	v_cndmask_b32_e64 v122, v122, v186, s[6:7]
	v_cndmask_b32_e64 v123, v123, v187, s[6:7]
	v_cndmask_b32_e64 v128, v161, v129, s[6:7]
	v_cvt_pk_bf16_f32 v126, v126, v127
	v_cvt_pk_bf16_f32 v127, v124, v128
	v_cvt_pk_bf16_f32 v124, v122, v123
	s_cbranch_vccnz .LBB0_149
	s_and_b64 s[0:1], s[6:7], exec
	s_cselect_b32 s1, s15, s13
	s_cselect_b32 s0, s14, s12
	v_lshl_add_u64 v[122:123], s[0:1], 0, v[158:159]
	s_lshl_b32 s46, s11, 8
	v_lshl_add_u64 v[122:123], v[122:123], 0, s[46:47]
	v_lshl_add_u64 v[122:123], v[122:123], 0, v[0:1]
	v_mov_b32_e32 v168, v124
	v_mov_b32_e32 v169, v125
	v_mov_b32_e32 v170, v126
	v_mov_b32_e32 v171, v127
	v_lshl_add_u64 v[172:173], v[122:123], 0, v[174:175]
	s_nop 0
	v_permlane16_swap_b32_e32 v168, v170
	v_permlane16_swap_b32_e32 v169, v171
	global_store_dwordx4 v[172:173], v[168:171], off

; __device__ __forceinline__ unsigned cvt_pk_bf16(float lo, float hi) { unsigned r; asm("v_cvt_pk_bf16_f32 %0, %1, %2" : "=v"(r) : "v"(lo), "v"(hi)); return r; }
;     __device__ __forceinline__ void operator()(const f32x4 (&acc)[2][2][4][2], const Unit& u, int wr, int wc, int fr, int fq) const {
;     ...
;                     for (int bj = 0; bj < 2; ++bj) {
;                         const int head = 2 * (pn & 3) + bj;
;                         const f32x4 x1 = acc[ai][bj][m][0], x2 = acc[ai][bj][m][1];
;                         f32x4 o1 = x1 * cs - x2 * sn, o2 = x1 * sn + x2 * cs;
;                         if (isk) { o1 = o1 * KSCALE; o2 = o2 * KSCALE; }
;                         u32x2 w1, w2; w1.x = cvt_pk_bf16(o1[0], o1[1]); w1.y = cvt_pk_bf16(o1[2], o1[3]); w2.x = cvt_pk_bf16(o2[0], o2[1]); w2.y = cvt_pk_bf16(o2[2], o2[3]);
;                         if (!ctx) { bf16_t* dp = (isk ? k : q) + (size_t)row * 1024 + head * 128 + d0; *(u32x2*)dp = w1; *(u32x2*)(dp + 64) = w2; }
.LBB0_151:
	v_pk_mul_f32 v[124:125], v[116:117], v[136:137]
	v_pk_mul_f32 v[126:127], v[114:115], v[134:135]
	v_pk_mul_f32 v[116:117], v[116:117], v[132:133]
	v_pk_mul_f32 v[114:115], v[114:115], v[130:131]
	v_pk_fma_f32 v[124:125], v[120:121], v[132:133], v[124:125] neg_lo:[0,0,1] neg_hi:[0,0,1]
	v_pk_fma_f32 v[126:127], v[118:119], v[130:131], v[126:127] neg_lo:[0,0,1] neg_hi:[0,0,1]
	v_pk_fma_f32 v[116:117], v[120:121], v[136:137], v[116:117]
	v_pk_fma_f32 v[114:115], v[118:119], v[134:135], v[114:115]
	v_pk_mul_f32 v[118:119], v[126:127], s[76:77] op_sel_hi:[1,0]
	v_pk_mul_f32 v[120:121], v[124:125], s[76:77] op_sel_hi:[1,0]
	v_pk_mul_f32 v[128:129], v[114:115], s[76:77] op_sel_hi:[1,0]
	v_pk_mul_f32 v[130:131], v[116:117], s[76:77] op_sel_hi:[1,0]
	s_or_b32 s40, s11, 1
	v_cndmask_b32_e64 v123, v116, v130, s[6:7]
	v_cndmask_b32_e64 v130, v117, v131, s[6:7]
	v_cndmask_b32_e64 v114, v114, v128, s[6:7]
	v_cndmask_b32_e64 v115, v115, v129, s[6:7]
	v_cndmask_b32_e64 v117, v124, v120, s[6:7]
	v_cndmask_b32_e64 v116, v126, v118, s[6:7]
	s_and_b64 vcc, exec, s[4:5]
	v_cndmask_b32_e64 v120, v125, v121, s[6:7]
	v_cndmask_b32_e64 v118, v127, v119, s[6:7]
	v_cvt_pk_bf16_f32 v116, v116, v118
	v_cvt_pk_bf16_f32 v117, v117, v120
	v_cvt_pk_bf16_f32 v114, v114, v115
	v_cvt_pk_bf16_f32 v115, v123, v130
	s_cbranch_vccnz .LBB0_155
	s_add_u32 s0, s24, s0
	s_addc_u32 s1, s25, s1
	v_lshl_add_u64 v[118:119], s[0:1], 0, v[158:159]
	s_lshl_b32 s46, s40, 8
	v_lshl_add_u64 v[118:119], v[118:119], 0, s[46:47]
	v_lshl_add_u64 v[118:119], v[118:119], 0, v[0:1]
	v_mov_b32_e32 v168, v114
	v_mov_b32_e32 v169, v115
	v_mov_b32_e32 v170, v116
	v_mov_b32_e32 v171, v117
	v_lshl_add_u64 v[172:173], v[118:119], 0, v[174:175]
	s_nop 0
	v_permlane16_swap_b32_e32 v168, v170
	v_permlane16_swap_b32_e32 v169, v171
	global_store_dwordx4 v[172:173], v[168:171], off
	s_and_b64 vcc, exec, s[8:9]
	s_cbranch_vccz .LBB0_156

; __device__ __forceinline__ unsigned cvt_pk_bf16(float lo, float hi) { unsigned r; asm("v_cvt_pk_bf16_f32 %0, %1, %2" : "=v"(r) : "v"(lo), "v"(hi)); return r; }
;     __device__ __forceinline__ void operator()(const f32x4 (&acc)[2][2][4][2], const Unit& u, int wr, int wc, int fr, int fq) const {
;     ...
;                     for (int bj = 0; bj < 2; ++bj) {
;                         const int head = 2 * (pn & 3) + bj;
;                         const f32x4 x1 = acc[ai][bj][m][0], x2 = acc[ai][bj][m][1];
;                         f32x4 o1 = x1 * cs - x2 * sn, o2 = x1 * sn + x2 * cs;
;                         if (isk) { o1 = o1 * KSCALE; o2 = o2 * KSCALE; }
;                         u32x2 w1, w2; w1.x = cvt_pk_bf16(o1[0], o1[1]); w1.y = cvt_pk_bf16(o1[2], o1[3]); w2.x = cvt_pk_bf16(o2[0], o2[1]); w2.y = cvt_pk_bf16(o2[2], o2[3]);
;                         if (!ctx) { bf16_t* dp = (isk ? k : q) + (size_t)row * 1024 + head * 128 + d0; *(u32x2*)dp = w1; *(u32x2*)(dp + 64) = w2; }
.LBB0_158:
	s_waitcnt vmcnt(0)
	v_pk_mul_f32 v[126:127], v[108:109], v[120:121]
	v_pk_mul_f32 v[128:129], v[106:107], v[118:119]
	v_pk_mul_f32 v[108:109], v[108:109], v[116:117]
	v_pk_mul_f32 v[106:107], v[106:107], v[114:115]
	v_pk_fma_f32 v[128:129], v[110:111], v[114:115], v[128:129] neg_lo:[0,0,1] neg_hi:[0,0,1]
	v_pk_fma_f32 v[126:127], v[112:113], v[116:117], v[126:127] neg_lo:[0,0,1] neg_hi:[0,0,1]
	v_pk_fma_f32 v[106:107], v[110:111], v[118:119], v[106:107]
	v_pk_fma_f32 v[108:109], v[112:113], v[120:121], v[108:109]
	v_ashrrev_i32_e32 v125, 31, v124
	v_pk_mul_f32 v[110:111], v[128:129], s[76:77] op_sel_hi:[1,0]
	v_pk_mul_f32 v[112:113], v[126:127], s[76:77] op_sel_hi:[1,0]
	v_pk_mul_f32 v[130:131], v[106:107], s[76:77] op_sel_hi:[1,0]
	v_pk_mul_f32 v[132:133], v[108:109], s[76:77] op_sel_hi:[1,0]
	v_lshlrev_b64 v[124:125], 11, v[124:125]
	v_cndmask_b32_e64 v123, v108, v132, s[6:7]
	v_cndmask_b32_e64 v132, v109, v133, s[6:7]
	v_cndmask_b32_e64 v106, v106, v130, s[6:7]
	v_cndmask_b32_e64 v107, v107, v131, s[6:7]
	v_cndmask_b32_e64 v109, v126, v112, s[6:7]
	v_cndmask_b32_e64 v108, v128, v110, s[6:7]
	s_and_b64 vcc, exec, s[4:5]
	v_cndmask_b32_e64 v112, v127, v113, s[6:7]
	v_cndmask_b32_e64 v110, v129, v111, s[6:7]
	v_cvt_pk_bf16_f32 v108, v108, v110
	v_cvt_pk_bf16_f32 v109, v109, v112
	v_cvt_pk_bf16_f32 v106, v106, v107
	v_cvt_pk_bf16_f32 v107, v123, v132
	s_cbranch_vccnz .LBB0_160
	s_and_b64 s[0:1], s[6:7], exec
	s_cselect_b32 s1, s15, s13
	s_cselect_b32 s0, s14, s12
	v_lshl_add_u64 v[110:111], s[0:1], 0, v[124:125]
	s_lshl_b32 s46, s11, 8
	v_lshl_add_u64 v[110:111], v[110:111], 0, s[46:47]
	v_lshl_add_u64 v[110:111], v[110:111], 0, v[0:1]
	v_mov_b32_e32 v168, v106
	v_mov_b32_e32 v169, v107
	v_mov_b32_e32 v170, v108
	v_mov_b32_e32 v171, v109
	v_lshl_add_u64 v[172:173], v[110:111], 0, v[174:175]
	s_nop 0
	v_permlane16_swap_b32_e32 v168, v170
	v_permlane16_swap_b32_e32 v169, v171
	global_store_dwordx4 v[172:173], v[168:171], off

; __device__ __forceinline__ unsigned cvt_pk_bf16(float lo, float hi) { unsigned r; asm("v_cvt_pk_bf16_f32 %0, %1, %2" : "=v"(r) : "v"(lo), "v"(hi)); return r; }
;     __device__ __forceinline__ void operator()(const f32x4 (&acc)[2][2][4][2], const Unit& u, int wr, int wc, int fr, int fq) const {
;     ...
;                     for (int bj = 0; bj < 2; ++bj) {
;                         const int head = 2 * (pn & 3) + bj;
;                         const f32x4 x1 = acc[ai][bj][m][0], x2 = acc[ai][bj][m][1];
;                         f32x4 o1 = x1 * cs - x2 * sn, o2 = x1 * sn + x2 * cs;
;                         if (isk) { o1 = o1 * KSCALE; o2 = o2 * KSCALE; }
;                         u32x2 w1, w2; w1.x = cvt_pk_bf16(o1[0], o1[1]); w1.y = cvt_pk_bf16(o1[2], o1[3]); w2.x = cvt_pk_bf16(o2[0], o2[1]); w2.y = cvt_pk_bf16(o2[2], o2[3]);
;                         if (!ctx) { bf16_t* dp = (isk ? k : q) + (size_t)row * 1024 + head * 128 + d0; *(u32x2*)dp = w1; *(u32x2*)(dp + 64) = w2; }
.LBB0_162:
	v_pk_mul_f32 v[106:107], v[100:101], v[120:121]
	v_pk_mul_f32 v[108:109], v[98:99], v[118:119]
	v_pk_mul_f32 v[100:101], v[100:101], v[116:117]
	v_pk_mul_f32 v[98:99], v[98:99], v[114:115]
	v_pk_fma_f32 v[106:107], v[104:105], v[116:117], v[106:107] neg_lo:[0,0,1] neg_hi:[0,0,1]
	v_pk_fma_f32 v[108:109], v[102:103], v[114:115], v[108:109] neg_lo:[0,0,1] neg_hi:[0,0,1]
	v_pk_fma_f32 v[100:101], v[104:105], v[120:121], v[100:101]
	v_pk_fma_f32 v[98:99], v[102:103], v[118:119], v[98:99]
	v_pk_mul_f32 v[102:103], v[108:109], s[76:77] op_sel_hi:[1,0]
	v_pk_mul_f32 v[104:105], v[106:107], s[76:77] op_sel_hi:[1,0]
	v_pk_mul_f32 v[110:111], v[98:99], s[76:77] op_sel_hi:[1,0]
	v_pk_mul_f32 v[112:113], v[100:101], s[76:77] op_sel_hi:[1,0]
	v_cndmask_b32_e64 v98, v98, v110, s[6:7]
	v_cndmask_b32_e64 v112, v100, v112, s[6:7]
	v_cndmask_b32_e64 v113, v101, v113, s[6:7]
	v_cndmask_b32_e64 v99, v99, v111, s[6:7]
	v_cndmask_b32_e64 v101, v106, v104, s[6:7]
	v_cndmask_b32_e64 v100, v108, v102, s[6:7]
	s_and_b64 vcc, exec, s[4:5]
	v_cndmask_b32_e64 v104, v107, v105, s[6:7]
	v_cndmask_b32_e64 v102, v109, v103, s[6:7]
	v_cvt_pk_bf16_f32 v100, v100, v102
	v_cvt_pk_bf16_f32 v101, v101, v104
	v_cvt_pk_bf16_f32 v98, v98, v99
	v_cvt_pk_bf16_f32 v99, v112, v113
	s_cbranch_vccnz .LBB0_166
	s_add_u32 s0, s24, s0
	s_addc_u32 s1, s25, s1
	v_lshl_add_u64 v[102:103], s[0:1], 0, v[124:125]
	s_lshl_b32 s46, s40, 8
	v_lshl_add_u64 v[102:103], v[102:103], 0, s[46:47]
	v_lshl_add_u64 v[102:103], v[102:103], 0, v[0:1]
	v_mov_b32_e32 v168, v98
	v_mov_b32_e32 v169, v99
	v_mov_b32_e32 v170, v100
	v_mov_b32_e32 v171, v101
	v_lshl_add_u64 v[172:173], v[102:103], 0, v[174:175]
	s_nop 0
	v_permlane16_swap_b32_e32 v168, v170
	v_permlane16_swap_b32_e32 v169, v171
	global_store_dwordx4 v[172:173], v[168:171], off
	s_and_b64 vcc, exec, s[8:9]
	s_cbranch_vccz .LBB0_167

; __device__ __forceinline__ unsigned cvt_pk_bf16(float lo, float hi) { unsigned r; asm("v_cvt_pk_bf16_f32 %0, %1, %2" : "=v"(r) : "v"(lo), "v"(hi)); return r; }
;     __device__ __forceinline__ void operator()(const f32x4 (&acc)[2][2][4][2], const Unit& u, int wr, int wc, int fr, int fq) const {
;     ...
;                     for (int bj = 0; bj < 2; ++bj) {
;                         const int head = 2 * (pn & 3) + bj;
;                         const f32x4 x1 = acc[ai][bj][m][0], x2 = acc[ai][bj][m][1];
;                         f32x4 o1 = x1 * cs - x2 * sn, o2 = x1 * sn + x2 * cs;
;                         if (isk) { o1 = o1 * KSCALE; o2 = o2 * KSCALE; }
;                         u32x2 w1, w2; w1.x = cvt_pk_bf16(o1[0], o1[1]); w1.y = cvt_pk_bf16(o1[2], o1[3]); w2.x = cvt_pk_bf16(o2[0], o2[1]); w2.y = cvt_pk_bf16(o2[2], o2[3]);
;                         if (!ctx) { bf16_t* dp = (isk ? k : q) + (size_t)row * 1024 + head * 128 + d0; *(u32x2*)dp = w1; *(u32x2*)(dp + 64) = w2; }
.LBB0_169:
	s_waitcnt vmcnt(0)
	v_pk_mul_f32 v[108:109], v[92:93], v[104:105]
	v_pk_mul_f32 v[110:111], v[90:91], v[102:103]
	v_pk_mul_f32 v[92:93], v[92:93], v[100:101]
	v_pk_mul_f32 v[90:91], v[90:91], v[98:99]
	v_pk_fma_f32 v[110:111], v[94:95], v[98:99], v[110:111] neg_lo:[0,0,1] neg_hi:[0,0,1]
	v_pk_fma_f32 v[108:109], v[96:97], v[100:101], v[108:109] neg_lo:[0,0,1] neg_hi:[0,0,1]
	v_pk_fma_f32 v[90:91], v[94:95], v[102:103], v[90:91]
	v_pk_fma_f32 v[92:93], v[96:97], v[104:105], v[92:93]
	v_ashrrev_i32_e32 v107, 31, v106
	v_pk_mul_f32 v[94:95], v[110:111], s[76:77] op_sel_hi:[1,0]
	v_pk_mul_f32 v[96:97], v[108:109], s[76:77] op_sel_hi:[1,0]
	v_pk_mul_f32 v[112:113], v[90:91], s[76:77] op_sel_hi:[1,0]
	v_pk_mul_f32 v[114:115], v[92:93], s[76:77] op_sel_hi:[1,0]
	v_lshlrev_b64 v[106:107], 11, v[106:107]
	v_cndmask_b32_e64 v114, v92, v114, s[6:7]
	v_cndmask_b32_e64 v115, v93, v115, s[6:7]
	v_cndmask_b32_e64 v90, v90, v112, s[6:7]
	v_cndmask_b32_e64 v91, v91, v113, s[6:7]
	v_cndmask_b32_e64 v93, v108, v96, s[6:7]
	v_cndmask_b32_e64 v92, v110, v94, s[6:7]
	s_and_b64 vcc, exec, s[4:5]
	v_cndmask_b32_e64 v96, v109, v97, s[6:7]
	v_cndmask_b32_e64 v94, v111, v95, s[6:7]
	v_cvt_pk_bf16_f32 v92, v92, v94
	v_cvt_pk_bf16_f32 v93, v93, v96
	v_cvt_pk_bf16_f32 v90, v90, v91
	v_cvt_pk_bf16_f32 v91, v114, v115
	s_cbranch_vccnz .LBB0_171
	s_and_b64 s[0:1], s[6:7], exec
	s_cselect_b32 s1, s15, s13
	s_cselect_b32 s0, s14, s12
	v_lshl_add_u64 v[94:95], s[0:1], 0, v[106:107]
	s_lshl_b32 s46, s11, 8
	v_lshl_add_u64 v[94:95], v[94:95], 0, s[46:47]
	v_lshl_add_u64 v[94:95], v[94:95], 0, v[0:1]
	v_mov_b32_e32 v168, v90
	v_mov_b32_e32 v169, v91
	v_mov_b32_e32 v170, v92
	v_mov_b32_e32 v171, v93
	v_lshl_add_u64 v[172:173], v[94:95], 0, v[174:175]
	s_nop 0
	v_permlane16_swap_b32_e32 v168, v170
	v_permlane16_swap_b32_e32 v169, v171
	global_store_dwordx4 v[172:173], v[168:171], off

; __device__ __forceinline__ unsigned cvt_pk_bf16(float lo, float hi) { unsigned r; asm("v_cvt_pk_bf16_f32 %0, %1, %2" : "=v"(r) : "v"(lo), "v"(hi)); return r; }
;     __device__ __forceinline__ void operator()(const f32x4 (&acc)[2][2][4][2], const Unit& u, int wr, int wc, int fr, int fq) const {
;     ...
;                     for (int bj = 0; bj < 2; ++bj) {
;                         const int head = 2 * (pn & 3) + bj;
;                         const f32x4 x1 = acc[ai][bj][m][0], x2 = acc[ai][bj][m][1];
;                         f32x4 o1 = x1 * cs - x2 * sn, o2 = x1 * sn + x2 * cs;
;                         if (isk) { o1 = o1 * KSCALE; o2 = o2 * KSCALE; }
;                         u32x2 w1, w2; w1.x = cvt_pk_bf16(o1[0], o1[1]); w1.y = cvt_pk_bf16(o1[2], o1[3]); w2.x = cvt_pk_bf16(o2[0], o2[1]); w2.y = cvt_pk_bf16(o2[2], o2[3]);
;                         if (!ctx) { bf16_t* dp = (isk ? k : q) + (size_t)row * 1024 + head * 128 + d0; *(u32x2*)dp = w1; *(u32x2*)(dp + 64) = w2; }
.LBB0_173:
	v_pk_mul_f32 v[90:91], v[84:85], v[104:105]
	v_pk_mul_f32 v[92:93], v[82:83], v[102:103]
	v_pk_mul_f32 v[84:85], v[84:85], v[100:101]
	v_pk_mul_f32 v[82:83], v[82:83], v[98:99]
	v_pk_fma_f32 v[90:91], v[88:89], v[100:101], v[90:91] neg_lo:[0,0,1] neg_hi:[0,0,1]
	v_pk_fma_f32 v[92:93], v[86:87], v[98:99], v[92:93] neg_lo:[0,0,1] neg_hi:[0,0,1]
	v_pk_fma_f32 v[84:85], v[88:89], v[104:105], v[84:85]
	v_pk_fma_f32 v[82:83], v[86:87], v[102:103], v[82:83]
	v_pk_mul_f32 v[86:87], v[92:93], s[76:77] op_sel_hi:[1,0]
	v_pk_mul_f32 v[88:89], v[90:91], s[76:77] op_sel_hi:[1,0]
	v_pk_mul_f32 v[94:95], v[82:83], s[76:77] op_sel_hi:[1,0]
	v_pk_mul_f32 v[96:97], v[84:85], s[76:77] op_sel_hi:[1,0]
	v_cndmask_b32_e64 v82, v82, v94, s[6:7]
	v_cndmask_b32_e64 v96, v84, v96, s[6:7]
	v_cndmask_b32_e64 v97, v85, v97, s[6:7]
	v_cndmask_b32_e64 v83, v83, v95, s[6:7]
	v_cndmask_b32_e64 v85, v90, v88, s[6:7]
	v_cndmask_b32_e64 v84, v92, v86, s[6:7]
	s_and_b64 vcc, exec, s[4:5]
	v_cndmask_b32_e64 v88, v91, v89, s[6:7]
	v_cndmask_b32_e64 v86, v93, v87, s[6:7]
	v_cvt_pk_bf16_f32 v84, v84, v86
	v_cvt_pk_bf16_f32 v85, v85, v88
	v_cvt_pk_bf16_f32 v82, v82, v83
	v_cvt_pk_bf16_f32 v83, v96, v97
	s_cbranch_vccnz .LBB0_177
	s_add_u32 s0, s24, s0
	s_addc_u32 s1, s25, s1
	v_lshl_add_u64 v[86:87], s[0:1], 0, v[106:107]
	s_lshl_b32 s46, s40, 8
	v_lshl_add_u64 v[86:87], v[86:87], 0, s[46:47]
	v_lshl_add_u64 v[86:87], v[86:87], 0, v[0:1]
	v_mov_b32_e32 v168, v82
	v_mov_b32_e32 v169, v83
	v_mov_b32_e32 v170, v84
	v_mov_b32_e32 v171, v85
	v_lshl_add_u64 v[172:173], v[86:87], 0, v[174:175]
	s_nop 0
	v_permlane16_swap_b32_e32 v168, v170
	v_permlane16_swap_b32_e32 v169, v171
	global_store_dwordx4 v[172:173], v[168:171], off
	s_and_b64 vcc, exec, s[8:9]
	s_cbranch_vccz .LBB0_178

; __device__ __forceinline__ unsigned cvt_pk_bf16(float lo, float hi) { unsigned r; asm("v_cvt_pk_bf16_f32 %0, %1, %2" : "=v"(r) : "v"(lo), "v"(hi)); return r; }
;     __device__ __forceinline__ void operator()(const f32x4 (&acc)[2][2][4][2], const Unit& u, int wr, int wc, int fr, int fq) const {
;     ...
;                     for (int bj = 0; bj < 2; ++bj) {
;                         const int head = 2 * (pn & 3) + bj;
;                         const f32x4 x1 = acc[ai][bj][m][0], x2 = acc[ai][bj][m][1];
;                         f32x4 o1 = x1 * cs - x2 * sn, o2 = x1 * sn + x2 * cs;
;                         if (isk) { o1 = o1 * KSCALE; o2 = o2 * KSCALE; }
;                         u32x2 w1, w2; w1.x = cvt_pk_bf16(o1[0], o1[1]); w1.y = cvt_pk_bf16(o1[2], o1[3]); w2.x = cvt_pk_bf16(o2[0], o2[1]); w2.y = cvt_pk_bf16(o2[2], o2[3]);
;                         if (!ctx) { bf16_t* dp = (isk ? k : q) + (size_t)row * 1024 + head * 128 + d0; *(u32x2*)dp = w1; *(u32x2*)(dp + 64) = w2; }
.LBB0_180:
	s_waitcnt vmcnt(0)
	v_pk_mul_f32 v[92:93], v[76:77], v[88:89]
	v_pk_mul_f32 v[94:95], v[74:75], v[86:87]
	v_pk_mul_f32 v[76:77], v[76:77], v[84:85]
	v_pk_mul_f32 v[74:75], v[74:75], v[82:83]
	v_pk_fma_f32 v[94:95], v[78:79], v[82:83], v[94:95] neg_lo:[0,0,1] neg_hi:[0,0,1]
	v_pk_fma_f32 v[92:93], v[80:81], v[84:85], v[92:93] neg_lo:[0,0,1] neg_hi:[0,0,1]
	v_pk_fma_f32 v[74:75], v[78:79], v[86:87], v[74:75]
	v_pk_fma_f32 v[76:77], v[80:81], v[88:89], v[76:77]
	v_ashrrev_i32_e32 v91, 31, v90
	v_pk_mul_f32 v[78:79], v[94:95], s[76:77] op_sel_hi:[1,0]
	v_pk_mul_f32 v[80:81], v[92:93], s[76:77] op_sel_hi:[1,0]
	v_pk_mul_f32 v[96:97], v[74:75], s[76:77] op_sel_hi:[1,0]
	v_pk_mul_f32 v[98:99], v[76:77], s[76:77] op_sel_hi:[1,0]
	v_lshlrev_b64 v[90:91], 11, v[90:91]
	v_cndmask_b32_e64 v98, v76, v98, s[6:7]
	v_cndmask_b32_e64 v99, v77, v99, s[6:7]
	v_cndmask_b32_e64 v74, v74, v96, s[6:7]
	v_cndmask_b32_e64 v75, v75, v97, s[6:7]
	v_cndmask_b32_e64 v77, v92, v80, s[6:7]
	v_cndmask_b32_e64 v76, v94, v78, s[6:7]
	s_and_b64 vcc, exec, s[4:5]
	v_cndmask_b32_e64 v80, v93, v81, s[6:7]
	v_cndmask_b32_e64 v78, v95, v79, s[6:7]
	v_cvt_pk_bf16_f32 v76, v76, v78
	v_cvt_pk_bf16_f32 v77, v77, v80
	v_cvt_pk_bf16_f32 v74, v74, v75
	v_cvt_pk_bf16_f32 v75, v98, v99
	s_cbranch_vccnz .LBB0_182
	s_and_b64 s[0:1], s[6:7], exec
	s_cselect_b32 s1, s15, s13
	s_cselect_b32 s0, s14, s12
	v_lshl_add_u64 v[78:79], s[0:1], 0, v[90:91]
	s_lshl_b32 s46, s11, 8
	v_lshl_add_u64 v[78:79], v[78:79], 0, s[46:47]
	v_lshl_add_u64 v[78:79], v[78:79], 0, v[0:1]
	v_mov_b32_e32 v168, v74
	v_mov_b32_e32 v169, v75
	v_mov_b32_e32 v170, v76
	v_mov_b32_e32 v171, v77
	v_lshl_add_u64 v[172:173], v[78:79], 0, v[174:175]
	s_nop 0
	v_permlane16_swap_b32_e32 v168, v170
	v_permlane16_swap_b32_e32 v169, v171
	global_store_dwordx4 v[172:173], v[168:171], off

; __device__ __forceinline__ unsigned cvt_pk_bf16(float lo, float hi) { unsigned r; asm("v_cvt_pk_bf16_f32 %0, %1, %2" : "=v"(r) : "v"(lo), "v"(hi)); return r; }
;     __device__ __forceinline__ void operator()(const f32x4 (&acc)[2][2][4][2], const Unit& u, int wr, int wc, int fr, int fq) const {
;     ...
;                     for (int bj = 0; bj < 2; ++bj) {
;                         const int head = 2 * (pn & 3) + bj;
;                         const f32x4 x1 = acc[ai][bj][m][0], x2 = acc[ai][bj][m][1];
;                         f32x4 o1 = x1 * cs - x2 * sn, o2 = x1 * sn + x2 * cs;
;                         if (isk) { o1 = o1 * KSCALE; o2 = o2 * KSCALE; }
;                         u32x2 w1, w2; w1.x = cvt_pk_bf16(o1[0], o1[1]); w1.y = cvt_pk_bf16(o1[2], o1[3]); w2.x = cvt_pk_bf16(o2[0], o2[1]); w2.y = cvt_pk_bf16(o2[2], o2[3]);
;                         if (!ctx) { bf16_t* dp = (isk ? k : q) + (size_t)row * 1024 + head * 128 + d0; *(u32x2*)dp = w1; *(u32x2*)(dp + 64) = w2; }
.LBB0_184:
	v_pk_mul_f32 v[74:75], v[68:69], v[88:89]
	v_pk_mul_f32 v[76:77], v[66:67], v[86:87]
	v_pk_mul_f32 v[68:69], v[68:69], v[84:85]
	v_pk_mul_f32 v[66:67], v[66:67], v[82:83]
	v_pk_fma_f32 v[74:75], v[72:73], v[84:85], v[74:75] neg_lo:[0,0,1] neg_hi:[0,0,1]
	v_pk_fma_f32 v[76:77], v[70:71], v[82:83], v[76:77] neg_lo:[0,0,1] neg_hi:[0,0,1]
	v_pk_fma_f32 v[68:69], v[72:73], v[88:89], v[68:69]
	v_pk_fma_f32 v[66:67], v[70:71], v[86:87], v[66:67]
	v_pk_mul_f32 v[70:71], v[76:77], s[76:77] op_sel_hi:[1,0]
	v_pk_mul_f32 v[72:73], v[74:75], s[76:77] op_sel_hi:[1,0]
	v_pk_mul_f32 v[78:79], v[66:67], s[76:77] op_sel_hi:[1,0]
	v_pk_mul_f32 v[80:81], v[68:69], s[76:77] op_sel_hi:[1,0]
	v_cndmask_b32_e64 v66, v66, v78, s[6:7]
	v_cndmask_b32_e64 v80, v68, v80, s[6:7]
	v_cndmask_b32_e64 v81, v69, v81, s[6:7]
	v_cndmask_b32_e64 v67, v67, v79, s[6:7]
	v_cndmask_b32_e64 v69, v74, v72, s[6:7]
	v_cndmask_b32_e64 v68, v76, v70, s[6:7]
	s_and_b64 vcc, exec, s[4:5]
	v_cndmask_b32_e64 v72, v75, v73, s[6:7]
	v_cndmask_b32_e64 v70, v77, v71, s[6:7]
	v_cvt_pk_bf16_f32 v68, v68, v70
	v_cvt_pk_bf16_f32 v69, v69, v72
	v_cvt_pk_bf16_f32 v66, v66, v67
	v_cvt_pk_bf16_f32 v67, v80, v81
	s_cbranch_vccnz .LBB0_188
	s_add_u32 s0, s24, s0
	s_addc_u32 s1, s25, s1
	v_lshl_add_u64 v[70:71], s[0:1], 0, v[90:91]
	s_lshl_b32 s46, s40, 8
	v_lshl_add_u64 v[70:71], v[70:71], 0, s[46:47]
	v_lshl_add_u64 v[70:71], v[70:71], 0, v[0:1]
	v_mov_b32_e32 v168, v66
	v_mov_b32_e32 v169, v67
	v_mov_b32_e32 v170, v68
	v_mov_b32_e32 v171, v69
	v_lshl_add_u64 v[172:173], v[70:71], 0, v[174:175]
	s_nop 0
	v_permlane16_swap_b32_e32 v168, v170
	v_permlane16_swap_b32_e32 v169, v171
	global_store_dwordx4 v[172:173], v[168:171], off
	s_and_b64 vcc, exec, s[8:9]
	s_cbranch_vccz .LBB0_189

; __device__ __forceinline__ unsigned cvt_pk_bf16(float lo, float hi) { unsigned r; asm("v_cvt_pk_bf16_f32 %0, %1, %2" : "=v"(r) : "v"(lo), "v"(hi)); return r; }
;     __device__ __forceinline__ void operator()(const f32x4 (&acc)[2][2][4][2], const Unit& u, int wr, int wc, int fr, int fq) const {
;     ...
;                     for (int bj = 0; bj < 2; ++bj) {
;                         const int head = 2 * (pn & 3) + bj;
;                         const f32x4 x1 = acc[ai][bj][m][0], x2 = acc[ai][bj][m][1];
;                         f32x4 o1 = x1 * cs - x2 * sn, o2 = x1 * sn + x2 * cs;
;                         if (isk) { o1 = o1 * KSCALE; o2 = o2 * KSCALE; }
;                         u32x2 w1, w2; w1.x = cvt_pk_bf16(o1[0], o1[1]); w1.y = cvt_pk_bf16(o1[2], o1[3]); w2.x = cvt_pk_bf16(o2[0], o2[1]); w2.y = cvt_pk_bf16(o2[2], o2[3]);
;                         if (!ctx) { bf16_t* dp = (isk ? k : q) + (size_t)row * 1024 + head * 128 + d0; *(u32x2*)dp = w1; *(u32x2*)(dp + 64) = w2; }
.LBB0_191:
	s_waitcnt vmcnt(0)
	v_pk_mul_f32 v[76:77], v[60:61], v[72:73]
	v_pk_mul_f32 v[78:79], v[58:59], v[70:71]
	v_pk_mul_f32 v[60:61], v[60:61], v[68:69]
	v_pk_mul_f32 v[58:59], v[58:59], v[66:67]
	v_pk_fma_f32 v[78:79], v[62:63], v[66:67], v[78:79] neg_lo:[0,0,1] neg_hi:[0,0,1]
	v_pk_fma_f32 v[76:77], v[64:65], v[68:69], v[76:77] neg_lo:[0,0,1] neg_hi:[0,0,1]
	v_pk_fma_f32 v[58:59], v[62:63], v[70:71], v[58:59]
	v_pk_fma_f32 v[60:61], v[64:65], v[72:73], v[60:61]
	v_ashrrev_i32_e32 v75, 31, v74
	v_pk_mul_f32 v[62:63], v[78:79], s[76:77] op_sel_hi:[1,0]
	v_pk_mul_f32 v[64:65], v[76:77], s[76:77] op_sel_hi:[1,0]
	v_pk_mul_f32 v[80:81], v[58:59], s[76:77] op_sel_hi:[1,0]
	v_pk_mul_f32 v[82:83], v[60:61], s[76:77] op_sel_hi:[1,0]
	v_lshlrev_b64 v[74:75], 11, v[74:75]
	v_cndmask_b32_e64 v82, v60, v82, s[6:7]
	v_cndmask_b32_e64 v83, v61, v83, s[6:7]
	v_cndmask_b32_e64 v58, v58, v80, s[6:7]
	v_cndmask_b32_e64 v59, v59, v81, s[6:7]
	v_cndmask_b32_e64 v61, v76, v64, s[6:7]
	v_cndmask_b32_e64 v60, v78, v62, s[6:7]
	s_and_b64 vcc, exec, s[4:5]
	v_cndmask_b32_e64 v64, v77, v65, s[6:7]
	v_cndmask_b32_e64 v62, v79, v63, s[6:7]
	v_cvt_pk_bf16_f32 v60, v60, v62
	v_cvt_pk_bf16_f32 v61, v61, v64
	v_cvt_pk_bf16_f32 v58, v58, v59
	v_cvt_pk_bf16_f32 v59, v82, v83
	s_cbranch_vccnz .LBB0_193
	s_and_b64 s[0:1], s[6:7], exec
	s_cselect_b32 s1, s15, s13
	s_cselect_b32 s0, s14, s12
	v_lshl_add_u64 v[62:63], s[0:1], 0, v[74:75]
	s_lshl_b32 s46, s11, 8
	v_lshl_add_u64 v[62:63], v[62:63], 0, s[46:47]
	v_lshl_add_u64 v[62:63], v[62:63], 0, v[0:1]
	v_mov_b32_e32 v168, v58
	v_mov_b32_e32 v169, v59
	v_mov_b32_e32 v170, v60
	v_mov_b32_e32 v171, v61
	v_lshl_add_u64 v[172:173], v[62:63], 0, v[174:175]
	s_nop 0
	v_permlane16_swap_b32_e32 v168, v170
	v_permlane16_swap_b32_e32 v169, v171
	global_store_dwordx4 v[172:173], v[168:171], off

; __device__ __forceinline__ unsigned cvt_pk_bf16(float lo, float hi) { unsigned r; asm("v_cvt_pk_bf16_f32 %0, %1, %2" : "=v"(r) : "v"(lo), "v"(hi)); return r; }
;     __device__ __forceinline__ void operator()(const f32x4 (&acc)[2][2][4][2], const Unit& u, int wr, int wc, int fr, int fq) const {
;     ...
;                     const int row = rbase + ai * HALF + m * 16, tt = wr * 64 + m * 16 + fr, cc = ccb + ai;
;                     f32x4 cs = {1.f, 1.f, 1.f, 1.f}, sn = {0.f, 0.f, 0.f, 0.f};
;                     if (!ctx) { const int t = row & (SEQ - 1); cs = *(const f32x4*)(rope + t * 64 + d0); sn = *(const f32x4*)(rope + SEQ * 64 + t * 64 + d0); }
; #pragma unroll
;                     for (int bj = 0; bj < 2; ++bj) {
;                         const int head = 2 * (pn & 3) + bj;
;                         const f32x4 x1 = acc[ai][bj][m][0], x2 = acc[ai][bj][m][1];
;                         f32x4 o1 = x1 * cs - x2 * sn, o2 = x1 * sn + x2 * cs;
;                         if (isk) { o1 = o1 * KSCALE; o2 = o2 * KSCALE; }
;                         u32x2 w1, w2; w1.x = cvt_pk_bf16(o1[0], o1[1]); w1.y = cvt_pk_bf16(o1[2], o1[3]); w2.x = cvt_pk_bf16(o2[0], o2[1]); w2.y = cvt_pk_bf16(o2[2], o2[3]);
;                         if (!ctx) { bf16_t* dp = (isk ? k : q) + (size_t)row * 1024 + head * 128 + d0; *(u32x2*)dp = w1; *(u32x2*)(dp + 64) = w2; }
.LBB0_195:
	v_pk_mul_f32 v[58:59], v[52:53], v[72:73]
	v_pk_mul_f32 v[60:61], v[50:51], v[70:71]
	v_pk_mul_f32 v[52:53], v[52:53], v[68:69]
	v_pk_mul_f32 v[50:51], v[50:51], v[66:67]
	v_pk_fma_f32 v[58:59], v[56:57], v[68:69], v[58:59] neg_lo:[0,0,1] neg_hi:[0,0,1]
	v_pk_fma_f32 v[60:61], v[54:55], v[66:67], v[60:61] neg_lo:[0,0,1] neg_hi:[0,0,1]
	v_pk_fma_f32 v[52:53], v[56:57], v[72:73], v[52:53]
	v_pk_fma_f32 v[50:51], v[54:55], v[70:71], v[50:51]
	v_pk_mul_f32 v[54:55], v[60:61], s[76:77] op_sel_hi:[1,0]
	v_pk_mul_f32 v[56:57], v[58:59], s[76:77] op_sel_hi:[1,0]
	v_pk_mul_f32 v[62:63], v[50:51], s[76:77] op_sel_hi:[1,0]
	v_pk_mul_f32 v[64:65], v[52:53], s[76:77] op_sel_hi:[1,0]
	v_cndmask_b32_e64 v50, v50, v62, s[6:7]
	v_cndmask_b32_e64 v64, v52, v64, s[6:7]
	v_cndmask_b32_e64 v65, v53, v65, s[6:7]
	v_cndmask_b32_e64 v51, v51, v63, s[6:7]
	v_cndmask_b32_e64 v53, v58, v56, s[6:7]
	v_cndmask_b32_e64 v52, v60, v54, s[6:7]
	s_and_b64 vcc, exec, s[4:5]
	v_cndmask_b32_e64 v56, v59, v57, s[6:7]
	v_cndmask_b32_e64 v54, v61, v55, s[6:7]
	v_cvt_pk_bf16_f32 v52, v52, v54
	v_cvt_pk_bf16_f32 v53, v53, v56
	v_cvt_pk_bf16_f32 v50, v50, v51
	v_cvt_pk_bf16_f32 v51, v64, v65
	s_cbranch_vccnz .LBB0_199
	s_add_u32 s0, s24, s0
	s_addc_u32 s1, s25, s1
	v_lshl_add_u64 v[54:55], s[0:1], 0, v[74:75]
	s_lshl_b32 s46, s40, 8
	v_lshl_add_u64 v[54:55], v[54:55], 0, s[46:47]
	v_lshl_add_u64 v[54:55], v[54:55], 0, v[0:1]
	v_mov_b32_e32 v168, v50
	v_mov_b32_e32 v169, v51
	v_mov_b32_e32 v170, v52
	v_mov_b32_e32 v171, v53
	v_lshl_add_u64 v[172:173], v[54:55], 0, v[174:175]
	s_nop 0
	v_permlane16_swap_b32_e32 v168, v170
	v_permlane16_swap_b32_e32 v169, v171
	global_store_dwordx4 v[172:173], v[168:171], off
	s_and_b64 vcc, exec, s[8:9]
	s_cbranch_vccz .LBB0_200

; __device__ __forceinline__ unsigned cvt_pk_bf16(float lo, float hi) { unsigned r; asm("v_cvt_pk_bf16_f32 %0, %1, %2" : "=v"(r) : "v"(lo), "v"(hi)); return r; }
;     __device__ __forceinline__ void operator()(const f32x4 (&acc)[2][2][4][2], const Unit& u, int wr, int wc, int fr, int fq) const {
;     ...
;                     const int row = rbase + ai * HALF + m * 16, tt = wr * 64 + m * 16 + fr, cc = ccb + ai;
;                     f32x4 cs = {1.f, 1.f, 1.f, 1.f}, sn = {0.f, 0.f, 0.f, 0.f};
;                     if (!ctx) { const int t = row & (SEQ - 1); cs = *(const f32x4*)(rope + t * 64 + d0); sn = *(const f32x4*)(rope + SEQ * 64 + t * 64 + d0); }
; #pragma unroll
;                     for (int bj = 0; bj < 2; ++bj) {
;                         const int head = 2 * (pn & 3) + bj;
;                         const f32x4 x1 = acc[ai][bj][m][0], x2 = acc[ai][bj][m][1];
;                         f32x4 o1 = x1 * cs - x2 * sn, o2 = x1 * sn + x2 * cs;
;                         if (isk) { o1 = o1 * KSCALE; o2 = o2 * KSCALE; }
;                         u32x2 w1, w2; w1.x = cvt_pk_bf16(o1[0], o1[1]); w1.y = cvt_pk_bf16(o1[2], o1[3]); w2.x = cvt_pk_bf16(o2[0], o2[1]); w2.y = cvt_pk_bf16(o2[2], o2[3]);
;                         if (!ctx) { bf16_t* dp = (isk ? k : q) + (size_t)row * 1024 + head * 128 + d0; *(u32x2*)dp = w1; *(u32x2*)(dp + 64) = w2; }
.LBB0_202:
	s_waitcnt vmcnt(0)
	v_pk_mul_f32 v[60:61], v[44:45], v[56:57]
	v_pk_mul_f32 v[62:63], v[42:43], v[54:55]
	v_pk_mul_f32 v[44:45], v[44:45], v[52:53]
	v_pk_mul_f32 v[42:43], v[42:43], v[50:51]
	v_pk_fma_f32 v[62:63], v[46:47], v[50:51], v[62:63] neg_lo:[0,0,1] neg_hi:[0,0,1]
	v_pk_fma_f32 v[60:61], v[48:49], v[52:53], v[60:61] neg_lo:[0,0,1] neg_hi:[0,0,1]
	v_pk_fma_f32 v[42:43], v[46:47], v[54:55], v[42:43]
	v_pk_fma_f32 v[44:45], v[48:49], v[56:57], v[44:45]
	v_ashrrev_i32_e32 v59, 31, v58
	v_pk_mul_f32 v[46:47], v[62:63], s[76:77] op_sel_hi:[1,0]
	v_pk_mul_f32 v[48:49], v[60:61], s[76:77] op_sel_hi:[1,0]
	v_pk_mul_f32 v[64:65], v[42:43], s[76:77] op_sel_hi:[1,0]
	v_pk_mul_f32 v[66:67], v[44:45], s[76:77] op_sel_hi:[1,0]
	v_lshlrev_b64 v[58:59], 11, v[58:59]
	v_cndmask_b32_e64 v66, v44, v66, s[6:7]
	v_cndmask_b32_e64 v67, v45, v67, s[6:7]
	v_cndmask_b32_e64 v42, v42, v64, s[6:7]
	v_cndmask_b32_e64 v43, v43, v65, s[6:7]
	v_cndmask_b32_e64 v45, v60, v48, s[6:7]
	v_cndmask_b32_e64 v44, v62, v46, s[6:7]
	s_and_b64 vcc, exec, s[4:5]
	v_cndmask_b32_e64 v48, v61, v49, s[6:7]
	v_cndmask_b32_e64 v46, v63, v47, s[6:7]
	v_cvt_pk_bf16_f32 v44, v44, v46
	v_cvt_pk_bf16_f32 v45, v45, v48
	v_cvt_pk_bf16_f32 v42, v42, v43
	v_cvt_pk_bf16_f32 v43, v66, v67
	s_cbranch_vccnz .LBB0_204
	s_and_b64 s[0:1], s[6:7], exec
	s_cselect_b32 s1, s15, s13
	s_cselect_b32 s0, s14, s12
	v_lshl_add_u64 v[46:47], s[0:1], 0, v[58:59]
	s_lshl_b32 s46, s11, 8
	v_lshl_add_u64 v[46:47], v[46:47], 0, s[46:47]
	v_lshl_add_u64 v[46:47], v[46:47], 0, v[0:1]
	v_mov_b32_e32 v168, v42
	v_mov_b32_e32 v169, v43
	v_mov_b32_e32 v170, v44
	v_mov_b32_e32 v171, v45
	v_lshl_add_u64 v[172:173], v[46:47], 0, v[174:175]
	s_nop 0
	v_permlane16_swap_b32_e32 v168, v170
	v_permlane16_swap_b32_e32 v169, v171
	global_store_dwordx4 v[172:173], v[168:171], off

; __device__ __forceinline__ unsigned cvt_pk_bf16(float lo, float hi) { unsigned r; asm("v_cvt_pk_bf16_f32 %0, %1, %2" : "=v"(r) : "v"(lo), "v"(hi)); return r; }
;     __device__ __forceinline__ void operator()(const f32x4 (&acc)[2][2][4][2], const Unit& u, int wr, int wc, int fr, int fq) const {
;     ...
;                     const int row = rbase + ai * HALF + m * 16, tt = wr * 64 + m * 16 + fr, cc = ccb + ai;
;                     f32x4 cs = {1.f, 1.f, 1.f, 1.f}, sn = {0.f, 0.f, 0.f, 0.f};
;                     if (!ctx) { const int t = row & (SEQ - 1); cs = *(const f32x4*)(rope + t * 64 + d0); sn = *(const f32x4*)(rope + SEQ * 64 + t * 64 + d0); }
; #pragma unroll
;                     for (int bj = 0; bj < 2; ++bj) {
;                         const int head = 2 * (pn & 3) + bj;
;                         const f32x4 x1 = acc[ai][bj][m][0], x2 = acc[ai][bj][m][1];
;                         f32x4 o1 = x1 * cs - x2 * sn, o2 = x1 * sn + x2 * cs;
;                         if (isk) { o1 = o1 * KSCALE; o2 = o2 * KSCALE; }
;                         u32x2 w1, w2; w1.x = cvt_pk_bf16(o1[0], o1[1]); w1.y = cvt_pk_bf16(o1[2], o1[3]); w2.x = cvt_pk_bf16(o2[0], o2[1]); w2.y = cvt_pk_bf16(o2[2], o2[3]);
;                         if (!ctx) { bf16_t* dp = (isk ? k : q) + (size_t)row * 1024 + head * 128 + d0; *(u32x2*)dp = w1; *(u32x2*)(dp + 64) = w2; }
.LBB0_206:
	v_pk_mul_f32 v[42:43], v[36:37], v[56:57]
	v_pk_mul_f32 v[44:45], v[34:35], v[54:55]
	v_pk_mul_f32 v[36:37], v[36:37], v[52:53]
	v_pk_mul_f32 v[34:35], v[34:35], v[50:51]
	v_pk_fma_f32 v[42:43], v[40:41], v[52:53], v[42:43] neg_lo:[0,0,1] neg_hi:[0,0,1]
	v_pk_fma_f32 v[44:45], v[38:39], v[50:51], v[44:45] neg_lo:[0,0,1] neg_hi:[0,0,1]
	v_pk_fma_f32 v[36:37], v[40:41], v[56:57], v[36:37]
	v_pk_fma_f32 v[34:35], v[38:39], v[54:55], v[34:35]
	v_pk_mul_f32 v[38:39], v[44:45], s[76:77] op_sel_hi:[1,0]
	v_pk_mul_f32 v[40:41], v[42:43], s[76:77] op_sel_hi:[1,0]
	v_pk_mul_f32 v[46:47], v[34:35], s[76:77] op_sel_hi:[1,0]
	v_pk_mul_f32 v[48:49], v[36:37], s[76:77] op_sel_hi:[1,0]
	v_cndmask_b32_e64 v34, v34, v46, s[6:7]
	v_cndmask_b32_e64 v48, v36, v48, s[6:7]
	v_cndmask_b32_e64 v49, v37, v49, s[6:7]
	v_cndmask_b32_e64 v35, v35, v47, s[6:7]
	v_cndmask_b32_e64 v37, v42, v40, s[6:7]
	v_cndmask_b32_e64 v36, v44, v38, s[6:7]
	s_and_b64 vcc, exec, s[4:5]
	v_cndmask_b32_e64 v40, v43, v41, s[6:7]
	v_cndmask_b32_e64 v38, v45, v39, s[6:7]
	v_cvt_pk_bf16_f32 v36, v36, v38
	v_cvt_pk_bf16_f32 v37, v37, v40
	v_cvt_pk_bf16_f32 v34, v34, v35
	v_cvt_pk_bf16_f32 v35, v48, v49
	s_cbranch_vccnz .LBB0_210
	s_add_u32 s0, s24, s0
	s_addc_u32 s1, s25, s1
	v_lshl_add_u64 v[38:39], s[0:1], 0, v[58:59]
	s_lshl_b32 s46, s40, 8
	v_lshl_add_u64 v[38:39], v[38:39], 0, s[46:47]
	v_lshl_add_u64 v[38:39], v[38:39], 0, v[0:1]
	v_mov_b32_e32 v168, v34
	v_mov_b32_e32 v169, v35
	v_mov_b32_e32 v170, v36
	v_mov_b32_e32 v171, v37
	v_lshl_add_u64 v[172:173], v[38:39], 0, v[174:175]
	s_nop 0
	v_permlane16_swap_b32_e32 v168, v170
	v_permlane16_swap_b32_e32 v169, v171
	global_store_dwordx4 v[172:173], v[168:171], off
	s_and_b64 vcc, exec, s[8:9]
	s_cbranch_vccz .LBB0_211

; __device__ __forceinline__ unsigned cvt_pk_bf16(float lo, float hi) { unsigned r; asm("v_cvt_pk_bf16_f32 %0, %1, %2" : "=v"(r) : "v"(lo), "v"(hi)); return r; }
;     __device__ __forceinline__ void operator()(const f32x4 (&acc)[2][2][4][2], const Unit& u, int wr, int wc, int fr, int fq) const {
;     ...
;                     const int row = rbase + ai * HALF + m * 16, tt = wr * 64 + m * 16 + fr, cc = ccb + ai;
;                     f32x4 cs = {1.f, 1.f, 1.f, 1.f}, sn = {0.f, 0.f, 0.f, 0.f};
;                     if (!ctx) { const int t = row & (SEQ - 1); cs = *(const f32x4*)(rope + t * 64 + d0); sn = *(const f32x4*)(rope + SEQ * 64 + t * 64 + d0); }
; #pragma unroll
;                     for (int bj = 0; bj < 2; ++bj) {
;                         const int head = 2 * (pn & 3) + bj;
;                         const f32x4 x1 = acc[ai][bj][m][0], x2 = acc[ai][bj][m][1];
;                         f32x4 o1 = x1 * cs - x2 * sn, o2 = x1 * sn + x2 * cs;
;                         if (isk) { o1 = o1 * KSCALE; o2 = o2 * KSCALE; }
;                         u32x2 w1, w2; w1.x = cvt_pk_bf16(o1[0], o1[1]); w1.y = cvt_pk_bf16(o1[2], o1[3]); w2.x = cvt_pk_bf16(o2[0], o2[1]); w2.y = cvt_pk_bf16(o2[2], o2[3]);
;                         if (!ctx) { bf16_t* dp = (isk ? k : q) + (size_t)row * 1024 + head * 128 + d0; *(u32x2*)dp = w1; *(u32x2*)(dp + 64) = w2; }
.LBB0_213:
	s_waitcnt vmcnt(0)
	v_pk_mul_f32 v[44:45], v[28:29], v[40:41]
	v_pk_mul_f32 v[46:47], v[26:27], v[38:39]
	v_pk_mul_f32 v[28:29], v[28:29], v[36:37]
	v_pk_mul_f32 v[26:27], v[26:27], v[34:35]
	v_pk_fma_f32 v[46:47], v[30:31], v[34:35], v[46:47] neg_lo:[0,0,1] neg_hi:[0,0,1]
	v_pk_fma_f32 v[44:45], v[32:33], v[36:37], v[44:45] neg_lo:[0,0,1] neg_hi:[0,0,1]
	v_pk_fma_f32 v[26:27], v[30:31], v[38:39], v[26:27]
	v_pk_fma_f32 v[28:29], v[32:33], v[40:41], v[28:29]
	v_ashrrev_i32_e32 v43, 31, v42
	v_pk_mul_f32 v[30:31], v[46:47], s[76:77] op_sel_hi:[1,0]
	v_pk_mul_f32 v[32:33], v[44:45], s[76:77] op_sel_hi:[1,0]
	v_pk_mul_f32 v[48:49], v[26:27], s[76:77] op_sel_hi:[1,0]
	v_pk_mul_f32 v[50:51], v[28:29], s[76:77] op_sel_hi:[1,0]
	v_lshlrev_b64 v[42:43], 11, v[42:43]
	v_cndmask_b32_e64 v50, v28, v50, s[6:7]
	v_cndmask_b32_e64 v51, v29, v51, s[6:7]
	v_cndmask_b32_e64 v26, v26, v48, s[6:7]
	v_cndmask_b32_e64 v27, v27, v49, s[6:7]
	v_cndmask_b32_e64 v29, v44, v32, s[6:7]
	v_cndmask_b32_e64 v28, v46, v30, s[6:7]
	s_and_b64 vcc, exec, s[4:5]
	v_cndmask_b32_e64 v32, v45, v33, s[6:7]
	v_cndmask_b32_e64 v30, v47, v31, s[6:7]
	v_cvt_pk_bf16_f32 v28, v28, v30
	v_cvt_pk_bf16_f32 v29, v29, v32
	v_cvt_pk_bf16_f32 v26, v26, v27
	v_cvt_pk_bf16_f32 v27, v50, v51
	s_cbranch_vccnz .LBB0_215
	s_and_b64 s[0:1], s[6:7], exec
	s_cselect_b32 s1, s15, s13
	s_cselect_b32 s0, s14, s12
	v_lshl_add_u64 v[30:31], s[0:1], 0, v[42:43]
	s_lshl_b32 s46, s11, 8
	v_lshl_add_u64 v[30:31], v[30:31], 0, s[46:47]
	v_lshl_add_u64 v[30:31], v[30:31], 0, v[0:1]
	v_mov_b32_e32 v168, v26
	v_mov_b32_e32 v169, v27
	v_mov_b32_e32 v170, v28
	v_mov_b32_e32 v171, v29
	v_lshl_add_u64 v[172:173], v[30:31], 0, v[174:175]
	s_nop 0
	v_permlane16_swap_b32_e32 v168, v170
	v_permlane16_swap_b32_e32 v169, v171
	global_store_dwordx4 v[172:173], v[168:171], off

; __device__ __forceinline__ unsigned cvt_pk_bf16(float lo, float hi) { unsigned r; asm("v_cvt_pk_bf16_f32 %0, %1, %2" : "=v"(r) : "v"(lo), "v"(hi)); return r; }
;     __device__ __forceinline__ void operator()(const f32x4 (&acc)[2][2][4][2], const Unit& u, int wr, int wc, int fr, int fq) const {
;     ...
;                     const int row = rbase + ai * HALF + m * 16, tt = wr * 64 + m * 16 + fr, cc = ccb + ai;
;                     f32x4 cs = {1.f, 1.f, 1.f, 1.f}, sn = {0.f, 0.f, 0.f, 0.f};
;                     if (!ctx) { const int t = row & (SEQ - 1); cs = *(const f32x4*)(rope + t * 64 + d0); sn = *(const f32x4*)(rope + SEQ * 64 + t * 64 + d0); }
; #pragma unroll
;                     for (int bj = 0; bj < 2; ++bj) {
;                         const int head = 2 * (pn & 3) + bj;
;                         const f32x4 x1 = acc[ai][bj][m][0], x2 = acc[ai][bj][m][1];
;                         f32x4 o1 = x1 * cs - x2 * sn, o2 = x1 * sn + x2 * cs;
;                         if (isk) { o1 = o1 * KSCALE; o2 = o2 * KSCALE; }
;                         u32x2 w1, w2; w1.x = cvt_pk_bf16(o1[0], o1[1]); w1.y = cvt_pk_bf16(o1[2], o1[3]); w2.x = cvt_pk_bf16(o2[0], o2[1]); w2.y = cvt_pk_bf16(o2[2], o2[3]);
;                         if (!ctx) { bf16_t* dp = (isk ? k : q) + (size_t)row * 1024 + head * 128 + d0; *(u32x2*)dp = w1; *(u32x2*)(dp + 64) = w2; }
.LBB0_217:
	v_pk_mul_f32 v[26:27], v[20:21], v[40:41]
	v_pk_mul_f32 v[28:29], v[18:19], v[38:39]
	v_pk_mul_f32 v[20:21], v[20:21], v[36:37]
	v_pk_mul_f32 v[18:19], v[18:19], v[34:35]
	v_pk_fma_f32 v[26:27], v[24:25], v[36:37], v[26:27] neg_lo:[0,0,1] neg_hi:[0,0,1]
	v_pk_fma_f32 v[28:29], v[22:23], v[34:35], v[28:29] neg_lo:[0,0,1] neg_hi:[0,0,1]
	v_pk_fma_f32 v[20:21], v[24:25], v[40:41], v[20:21]
	v_pk_fma_f32 v[18:19], v[22:23], v[38:39], v[18:19]
	v_pk_mul_f32 v[22:23], v[28:29], s[76:77] op_sel_hi:[1,0]
	v_pk_mul_f32 v[24:25], v[26:27], s[76:77] op_sel_hi:[1,0]
	v_pk_mul_f32 v[30:31], v[18:19], s[76:77] op_sel_hi:[1,0]
	v_pk_mul_f32 v[32:33], v[20:21], s[76:77] op_sel_hi:[1,0]
	v_cndmask_b32_e64 v18, v18, v30, s[6:7]
	v_cndmask_b32_e64 v32, v20, v32, s[6:7]
	v_cndmask_b32_e64 v33, v21, v33, s[6:7]
	v_cndmask_b32_e64 v19, v19, v31, s[6:7]
	v_cndmask_b32_e64 v21, v26, v24, s[6:7]
	v_cndmask_b32_e64 v20, v28, v22, s[6:7]
	s_and_b64 vcc, exec, s[4:5]
	v_cndmask_b32_e64 v24, v27, v25, s[6:7]
	v_cndmask_b32_e64 v22, v29, v23, s[6:7]
	v_cvt_pk_bf16_f32 v20, v20, v22
	v_cvt_pk_bf16_f32 v21, v21, v24
	v_cvt_pk_bf16_f32 v18, v18, v19
	v_cvt_pk_bf16_f32 v19, v32, v33
	s_cbranch_vccnz .LBB0_221
	s_add_u32 s0, s24, s0
	s_addc_u32 s1, s25, s1
	v_lshl_add_u64 v[22:23], s[0:1], 0, v[42:43]
	s_lshl_b32 s46, s40, 8
	v_lshl_add_u64 v[22:23], v[22:23], 0, s[46:47]
	v_lshl_add_u64 v[22:23], v[22:23], 0, v[0:1]
	v_mov_b32_e32 v168, v18
	v_mov_b32_e32 v169, v19
	v_mov_b32_e32 v170, v20
	v_mov_b32_e32 v171, v21
	v_lshl_add_u64 v[172:173], v[22:23], 0, v[174:175]
	s_nop 0
	v_permlane16_swap_b32_e32 v168, v170
	v_permlane16_swap_b32_e32 v169, v171
	global_store_dwordx4 v[172:173], v[168:171], off
	s_and_b64 vcc, exec, s[8:9]
	s_cbranch_vccz .LBB0_222

; __device__ __forceinline__ unsigned cvt_pk_bf16(float lo, float hi) { unsigned r; asm("v_cvt_pk_bf16_f32 %0, %1, %2" : "=v"(r) : "v"(lo), "v"(hi)); return r; }
;     __device__ __forceinline__ void operator()(const f32x4 (&acc)[2][2][4][2], const Unit& u, int wr, int wc, int fr, int fq) const {
;     ...
;                     const int row = rbase + ai * HALF + m * 16, tt = wr * 64 + m * 16 + fr, cc = ccb + ai;
;                     f32x4 cs = {1.f, 1.f, 1.f, 1.f}, sn = {0.f, 0.f, 0.f, 0.f};
;                     if (!ctx) { const int t = row & (SEQ - 1); cs = *(const f32x4*)(rope + t * 64 + d0); sn = *(const f32x4*)(rope + SEQ * 64 + t * 64 + d0); }
; #pragma unroll
;                     for (int bj = 0; bj < 2; ++bj) {
;                         const int head = 2 * (pn & 3) + bj;
;                         const f32x4 x1 = acc[ai][bj][m][0], x2 = acc[ai][bj][m][1];
;                         f32x4 o1 = x1 * cs - x2 * sn, o2 = x1 * sn + x2 * cs;
;                         if (isk) { o1 = o1 * KSCALE; o2 = o2 * KSCALE; }
;                         u32x2 w1, w2; w1.x = cvt_pk_bf16(o1[0], o1[1]); w1.y = cvt_pk_bf16(o1[2], o1[3]); w2.x = cvt_pk_bf16(o2[0], o2[1]); w2.y = cvt_pk_bf16(o2[2], o2[3]);
;                         if (!ctx) { bf16_t* dp = (isk ? k : q) + (size_t)row * 1024 + head * 128 + d0; *(u32x2*)dp = w1; *(u32x2*)(dp + 64) = w2; }
.LBB0_224:
	s_waitcnt vmcnt(0)
	v_pk_mul_f32 v[28:29], v[12:13], v[24:25]
	v_pk_mul_f32 v[30:31], v[10:11], v[22:23]
	v_pk_mul_f32 v[12:13], v[12:13], v[20:21]
	v_pk_mul_f32 v[10:11], v[10:11], v[18:19]
	v_pk_fma_f32 v[30:31], v[14:15], v[18:19], v[30:31] neg_lo:[0,0,1] neg_hi:[0,0,1]
	v_pk_fma_f32 v[28:29], v[16:17], v[20:21], v[28:29] neg_lo:[0,0,1] neg_hi:[0,0,1]
	v_pk_fma_f32 v[10:11], v[14:15], v[22:23], v[10:11]
	v_pk_fma_f32 v[12:13], v[16:17], v[24:25], v[12:13]
	v_ashrrev_i32_e32 v27, 31, v26
	v_pk_mul_f32 v[14:15], v[30:31], s[76:77] op_sel_hi:[1,0]
	v_pk_mul_f32 v[16:17], v[28:29], s[76:77] op_sel_hi:[1,0]
	v_pk_mul_f32 v[32:33], v[10:11], s[76:77] op_sel_hi:[1,0]
	v_pk_mul_f32 v[34:35], v[12:13], s[76:77] op_sel_hi:[1,0]
	v_lshlrev_b64 v[26:27], 11, v[26:27]
	v_cndmask_b32_e64 v34, v12, v34, s[6:7]
	v_cndmask_b32_e64 v35, v13, v35, s[6:7]
	v_cndmask_b32_e64 v10, v10, v32, s[6:7]
	v_cndmask_b32_e64 v11, v11, v33, s[6:7]
	v_cndmask_b32_e64 v13, v28, v16, s[6:7]
	v_cndmask_b32_e64 v12, v30, v14, s[6:7]
	s_and_b64 vcc, exec, s[4:5]
	v_cndmask_b32_e64 v16, v29, v17, s[6:7]
	v_cndmask_b32_e64 v14, v31, v15, s[6:7]
	v_cvt_pk_bf16_f32 v12, v12, v14
	v_cvt_pk_bf16_f32 v13, v13, v16
	v_cvt_pk_bf16_f32 v10, v10, v11
	v_cvt_pk_bf16_f32 v11, v34, v35
	s_cbranch_vccnz .LBB0_226
	s_and_b64 s[0:1], s[6:7], exec
	s_cselect_b32 s1, s15, s13
	s_cselect_b32 s0, s14, s12
	v_lshl_add_u64 v[14:15], s[0:1], 0, v[26:27]
	s_lshl_b32 s46, s11, 8
	v_lshl_add_u64 v[14:15], v[14:15], 0, s[46:47]
	v_lshl_add_u64 v[14:15], v[14:15], 0, v[0:1]
	v_mov_b32_e32 v168, v10
	v_mov_b32_e32 v169, v11
	v_mov_b32_e32 v170, v12
	v_mov_b32_e32 v171, v13
	v_lshl_add_u64 v[172:173], v[14:15], 0, v[174:175]
	s_nop 0
	v_permlane16_swap_b32_e32 v168, v170
	v_permlane16_swap_b32_e32 v169, v171
	global_store_dwordx4 v[172:173], v[168:171], off

; __device__ __forceinline__ unsigned cvt_pk_bf16(float lo, float hi) { unsigned r; asm("v_cvt_pk_bf16_f32 %0, %1, %2" : "=v"(r) : "v"(lo), "v"(hi)); return r; }
;     __device__ __forceinline__ void operator()(const f32x4 (&acc)[2][2][4][2], const Unit& u, int wr, int wc, int fr, int fq) const {
;     ...
;                     const int row = rbase + ai * HALF + m * 16, tt = wr * 64 + m * 16 + fr, cc = ccb + ai;
;                     f32x4 cs = {1.f, 1.f, 1.f, 1.f}, sn = {0.f, 0.f, 0.f, 0.f};
;                     if (!ctx) { const int t = row & (SEQ - 1); cs = *(const f32x4*)(rope + t * 64 + d0); sn = *(const f32x4*)(rope + SEQ * 64 + t * 64 + d0); }
; #pragma unroll
;                     for (int bj = 0; bj < 2; ++bj) {
;                         const int head = 2 * (pn & 3) + bj;
;                         const f32x4 x1 = acc[ai][bj][m][0], x2 = acc[ai][bj][m][1];
;                         f32x4 o1 = x1 * cs - x2 * sn, o2 = x1 * sn + x2 * cs;
;                         if (isk) { o1 = o1 * KSCALE; o2 = o2 * KSCALE; }
;                         u32x2 w1, w2; w1.x = cvt_pk_bf16(o1[0], o1[1]); w1.y = cvt_pk_bf16(o1[2], o1[3]); w2.x = cvt_pk_bf16(o2[0], o2[1]); w2.y = cvt_pk_bf16(o2[2], o2[3]);
;                         if (!ctx) { bf16_t* dp = (isk ? k : q) + (size_t)row * 1024 + head * 128 + d0; *(u32x2*)dp = w1; *(u32x2*)(dp + 64) = w2; }
.LBB0_228:
	v_pk_mul_f32 v[10:11], v[4:5], v[24:25]
	v_pk_mul_f32 v[12:13], v[2:3], v[22:23]
	v_pk_mul_f32 v[4:5], v[4:5], v[20:21]
	v_pk_mul_f32 v[2:3], v[2:3], v[18:19]
	v_pk_fma_f32 v[10:11], v[8:9], v[20:21], v[10:11] neg_lo:[0,0,1] neg_hi:[0,0,1]
	v_pk_fma_f32 v[12:13], v[6:7], v[18:19], v[12:13] neg_lo:[0,0,1] neg_hi:[0,0,1]
	v_pk_fma_f32 v[4:5], v[8:9], v[24:25], v[4:5]
	v_pk_fma_f32 v[2:3], v[6:7], v[22:23], v[2:3]
	v_pk_mul_f32 v[6:7], v[12:13], s[76:77] op_sel_hi:[1,0]
	v_pk_mul_f32 v[8:9], v[10:11], s[76:77] op_sel_hi:[1,0]
	v_pk_mul_f32 v[14:15], v[2:3], s[76:77] op_sel_hi:[1,0]
	v_pk_mul_f32 v[16:17], v[4:5], s[76:77] op_sel_hi:[1,0]
	v_cndmask_b32_e64 v2, v2, v14, s[6:7]
	v_cndmask_b32_e64 v16, v4, v16, s[6:7]
	v_cndmask_b32_e64 v17, v5, v17, s[6:7]
	v_cndmask_b32_e64 v3, v3, v15, s[6:7]
	v_cndmask_b32_e64 v5, v10, v8, s[6:7]
	v_cndmask_b32_e64 v4, v12, v6, s[6:7]
	s_and_b64 vcc, exec, s[4:5]
	v_cndmask_b32_e64 v8, v11, v9, s[6:7]
	v_cndmask_b32_e64 v6, v13, v7, s[6:7]
	v_cvt_pk_bf16_f32 v4, v4, v6
	v_cvt_pk_bf16_f32 v5, v5, v8
	v_cvt_pk_bf16_f32 v2, v2, v3
	v_cvt_pk_bf16_f32 v3, v16, v17
	s_cbranch_vccnz .LBB0_230
	s_add_u32 s0, s24, s0
	s_addc_u32 s1, s25, s1
	v_lshl_add_u64 v[6:7], s[0:1], 0, v[26:27]
	s_lshl_b32 s46, s40, 8
	v_lshl_add_u64 v[6:7], v[6:7], 0, s[46:47]
	v_lshl_add_u64 v[6:7], v[6:7], 0, v[0:1]
	v_mov_b32_e32 v168, v2
	v_mov_b32_e32 v169, v3
	v_mov_b32_e32 v170, v4
	v_mov_b32_e32 v171, v5
	v_lshl_add_u64 v[172:173], v[6:7], 0, v[174:175]
	s_nop 0
	v_permlane16_swap_b32_e32 v168, v170
	v_permlane16_swap_b32_e32 v169, v171
	global_store_dwordx4 v[172:173], v[168:171], off
